# GEMM K-loops: all s_setprio removed (no priority), A/B against the static raise
# baseline (speedup 1.0000x reference)
.LBB0_127:
	s_ashr_i32 s13, s12, 31
	s_lshl_b64 s[0:1], s[12:13], 19
	s_add_u32 s42, s6, s0
	v_cmp_lt_i64_e32 vcc, s[34:35], v[236:237]
	s_addc_u32 s43, s7, s1
	s_and_b64 s[0:1], vcc, exec
	s_cselect_b32 s0, s43, s19
	s_cselect_b32 s1, s42, s18
	s_ashr_i32 s31, s30, 31
	s_lshl_b64 s[24:25], s[30:31], 19
	s_add_u32 s44, s16, s24
	s_addc_u32 s45, s17, s25
	s_and_b64 s[24:25], vcc, exec
	s_cselect_b32 s13, s45, s15
	s_cselect_b32 s24, s44, s14
	s_add_u32 vcc_lo, s18, 0x40080
	s_addc_u32 vcc_hi, s19, 0
	s_add_u32 s25, s14, 0x100
	v_mov_b32_e32 v0, 0
	s_addc_u32 s31, s15, 0
	s_mov_b32 s34, -2
	v_mov_b32_e32 v1, v0
	v_mov_b32_e32 v2, v0
	v_mov_b32_e32 v3, v0
	v_mov_b32_e32 v4, v0
	v_mov_b32_e32 v5, v0
	v_mov_b32_e32 v6, v0
	v_mov_b32_e32 v7, v0
	v_mov_b32_e32 v16, v0
	v_mov_b32_e32 v17, v0
	v_mov_b32_e32 v18, v0
	v_mov_b32_e32 v19, v0
	v_mov_b32_e32 v20, v0
	v_mov_b32_e32 v21, v0
	v_mov_b32_e32 v22, v0
	v_mov_b32_e32 v23, v0
	v_mov_b32_e32 v32, v0
	v_mov_b32_e32 v33, v0
	v_mov_b32_e32 v34, v0
	v_mov_b32_e32 v35, v0
	v_mov_b32_e32 v36, v0
	v_mov_b32_e32 v37, v0
	v_mov_b32_e32 v38, v0
	v_mov_b32_e32 v39, v0
	v_mov_b32_e32 v48, v0
	v_mov_b32_e32 v49, v0
	v_mov_b32_e32 v50, v0
	v_mov_b32_e32 v51, v0
	v_mov_b32_e32 v52, v0
	v_mov_b32_e32 v53, v0
	v_mov_b32_e32 v54, v0
	v_mov_b32_e32 v55, v0
	v_mov_b32_e32 v8, v0
	v_mov_b32_e32 v9, v0
	v_mov_b32_e32 v10, v0
	v_mov_b32_e32 v11, v0
	v_mov_b32_e32 v12, v0
	v_mov_b32_e32 v13, v0
	v_mov_b32_e32 v14, v0
	v_mov_b32_e32 v15, v0
	v_mov_b32_e32 v24, v0
	v_mov_b32_e32 v25, v0
	v_mov_b32_e32 v26, v0
	v_mov_b32_e32 v27, v0
	v_mov_b32_e32 v28, v0
	v_mov_b32_e32 v29, v0
	v_mov_b32_e32 v30, v0
	v_mov_b32_e32 v31, v0
	v_mov_b32_e32 v40, v0
	v_mov_b32_e32 v41, v0
	v_mov_b32_e32 v42, v0
	v_mov_b32_e32 v43, v0
	v_mov_b32_e32 v44, v0
	v_mov_b32_e32 v45, v0
	v_mov_b32_e32 v46, v0
	v_mov_b32_e32 v47, v0
	v_mov_b32_e32 v56, v0
	v_mov_b32_e32 v57, v0
	v_mov_b32_e32 v58, v0
	v_mov_b32_e32 v59, v0
	v_mov_b32_e32 v60, v0
	v_mov_b32_e32 v61, v0
	v_mov_b32_e32 v62, v0
	v_mov_b32_e32 v63, v0
	v_mov_b32_e32 v64, v0
	v_mov_b32_e32 v65, v0
	v_mov_b32_e32 v66, v0
	v_mov_b32_e32 v67, v0
	v_mov_b32_e32 v68, v0
	v_mov_b32_e32 v69, v0
	v_mov_b32_e32 v70, v0
	v_mov_b32_e32 v71, v0
	v_mov_b32_e32 v80, v0
	v_mov_b32_e32 v81, v0
	v_mov_b32_e32 v82, v0
	v_mov_b32_e32 v83, v0
	v_mov_b32_e32 v84, v0
	v_mov_b32_e32 v85, v0
	v_mov_b32_e32 v86, v0
	v_mov_b32_e32 v87, v0
	v_mov_b32_e32 v96, v0
	v_mov_b32_e32 v97, v0
	v_mov_b32_e32 v98, v0
	v_mov_b32_e32 v99, v0
	v_mov_b32_e32 v100, v0
	v_mov_b32_e32 v101, v0
	v_mov_b32_e32 v102, v0
	v_mov_b32_e32 v103, v0
	v_mov_b32_e32 v112, v0
	v_mov_b32_e32 v113, v0
	v_mov_b32_e32 v114, v0
	v_mov_b32_e32 v115, v0
	v_mov_b32_e32 v116, v0
	v_mov_b32_e32 v117, v0
	v_mov_b32_e32 v118, v0
	v_mov_b32_e32 v119, v0
	v_mov_b32_e32 v72, v0
	v_mov_b32_e32 v73, v0
	v_mov_b32_e32 v74, v0
	v_mov_b32_e32 v75, v0
	v_mov_b32_e32 v76, v0
	v_mov_b32_e32 v77, v0
	v_mov_b32_e32 v78, v0
	v_mov_b32_e32 v79, v0
	v_mov_b32_e32 v88, v0
	v_mov_b32_e32 v89, v0
	v_mov_b32_e32 v90, v0
	v_mov_b32_e32 v91, v0
	v_mov_b32_e32 v92, v0
	v_mov_b32_e32 v93, v0
	v_mov_b32_e32 v94, v0
	v_mov_b32_e32 v95, v0
	v_mov_b32_e32 v104, v0
	v_mov_b32_e32 v105, v0
	v_mov_b32_e32 v106, v0
	v_mov_b32_e32 v107, v0
	v_mov_b32_e32 v108, v0
	v_mov_b32_e32 v109, v0
	v_mov_b32_e32 v110, v0
	v_mov_b32_e32 v111, v0
	v_mov_b32_e32 v120, v0
	v_mov_b32_e32 v121, v0
	v_mov_b32_e32 v122, v0
	v_mov_b32_e32 v123, v0
	v_mov_b32_e32 v124, v0
	v_mov_b32_e32 v125, v0
	v_mov_b32_e32 v126, v0
	v_mov_b32_e32 v127, v0
	s_cmpk_gt_u32 s50, 0xff
	s_cbranch_scc0 .Lgout_enter
	s_barrier
.Lgout_enter:
.LBB0_128:
	s_add_u32 s14, vcc_lo, 0xfffc0080
	s_addc_u32 s15, vcc_hi, -1
	s_add_i32 s20, 16, 0x10000
	v_add_u32_e32 v130, s20, v160
	ds_read_b128 v[154:157], v130
	ds_read_b128 v[164:167], v130 offset:1024
	ds_read_b128 v[168:171], v130 offset:2048
	ds_read_b128 v[172:175], v130 offset:3072
	s_cmp_eq_u32 s34, 12
	s_cselect_b32 s19, s0, s15
	s_cselect_b32 s18, s1, s14
	s_cselect_b32 s15, s13, s31
	s_cselect_b32 s14, s24, s25
	v_lshl_add_u64 v[130:131], vcc, 0, v[150:151]
	s_add_i32 m0, s9, 0xc000
	ds_read_b128 v[176:179], v162
	ds_read_b128 v[180:183], v162 offset:1024
	ds_read_b128 v[184:187], v162 offset:2048
	ds_read_b128 v[188:191], v162 offset:3072
	ds_read_b128 v[192:195], v162 offset:4096
	ds_read_b128 v[196:199], v162 offset:5120
	ds_read_b128 v[200:203], v162 offset:6144
	ds_read_b128 v[204:207], v162 offset:7168
	global_load_lds_dwordx4 v[130:131], off
	v_lshl_add_u64 v[130:131], vcc, 0, v[152:153]
	s_add_i32 m0, s9, 0xe000
	s_nop 0
	global_load_lds_dwordx4 v[130:131], off
	s_add_i32 s35, 16, 0x14000
	v_add_u32_e32 v130, s35, v160
	ds_read_b128 v[208:211], v130
	ds_read_b128 v[212:215], v130 offset:1024
	ds_read_b128 v[216:219], v130 offset:2048
	ds_read_b128 v[220:223], v130 offset:3072
	s_waitcnt vmcnt(8) lgkmcnt(0)
	s_barrier
	v_mfma_f32_16x16x32_bf16 v[124:127], v[154:157], v[176:179], v[124:127]
	v_mfma_f32_16x16x32_bf16 v[120:123], v[168:171], v[176:179], v[120:123]
	v_mfma_f32_16x16x32_bf16 v[108:111], v[154:157], v[184:187], v[108:111]
	v_mfma_f32_16x16x32_bf16 v[104:107], v[168:171], v[184:187], v[104:107]
	v_mfma_f32_16x16x32_bf16 v[92:95], v[154:157], v[192:195], v[92:95]
	v_mfma_f32_16x16x32_bf16 v[88:91], v[168:171], v[192:195], v[88:91]
	v_mfma_f32_16x16x32_bf16 v[76:79], v[154:157], v[200:203], v[76:79]
	v_mfma_f32_16x16x32_bf16 v[72:75], v[168:171], v[200:203], v[72:75]
	v_mfma_f32_16x16x32_bf16 v[124:127], v[164:167], v[180:183], v[124:127]
	v_mfma_f32_16x16x32_bf16 v[120:123], v[172:175], v[180:183], v[120:123]
	v_mfma_f32_16x16x32_bf16 v[108:111], v[164:167], v[188:191], v[108:111]
	v_mfma_f32_16x16x32_bf16 v[104:107], v[172:175], v[188:191], v[104:107]
	v_mfma_f32_16x16x32_bf16 v[92:95], v[164:167], v[196:199], v[92:95]
	v_mfma_f32_16x16x32_bf16 v[88:91], v[172:175], v[196:199], v[88:91]
	v_mfma_f32_16x16x32_bf16 v[76:79], v[164:167], v[204:207], v[76:79]
	v_mfma_f32_16x16x32_bf16 v[72:75], v[172:175], v[204:207], v[72:75]
	v_mfma_f32_16x16x32_bf16 v[116:119], v[208:211], v[176:179], v[116:119]
	v_mfma_f32_16x16x32_bf16 v[112:115], v[216:219], v[176:179], v[112:115]
	v_mfma_f32_16x16x32_bf16 v[100:103], v[208:211], v[184:187], v[100:103]
	v_mfma_f32_16x16x32_bf16 v[96:99], v[216:219], v[184:187], v[96:99]
	v_mfma_f32_16x16x32_bf16 v[84:87], v[208:211], v[192:195], v[84:87]
	v_mfma_f32_16x16x32_bf16 v[80:83], v[216:219], v[192:195], v[80:83]
	v_mfma_f32_16x16x32_bf16 v[68:71], v[208:211], v[200:203], v[68:71]
	v_mfma_f32_16x16x32_bf16 v[64:67], v[216:219], v[200:203], v[64:67]
	v_mfma_f32_16x16x32_bf16 v[116:119], v[212:215], v[180:183], v[116:119]
	v_mfma_f32_16x16x32_bf16 v[112:115], v[220:223], v[180:183], v[112:115]
	v_mfma_f32_16x16x32_bf16 v[100:103], v[212:215], v[188:191], v[100:103]
	v_mfma_f32_16x16x32_bf16 v[96:99], v[220:223], v[188:191], v[96:99]
	v_mfma_f32_16x16x32_bf16 v[84:87], v[212:215], v[196:199], v[84:87]
	v_mfma_f32_16x16x32_bf16 v[80:83], v[220:223], v[196:199], v[80:83]
	v_mfma_f32_16x16x32_bf16 v[68:71], v[212:215], v[204:207], v[68:71]
	v_mfma_f32_16x16x32_bf16 v[64:67], v[220:223], v[204:207], v[64:67]
	s_barrier
	ds_read_b128 v[176:179], v162 offset:16384
	ds_read_b128 v[180:183], v162 offset:17408
	ds_read_b128 v[184:187], v162 offset:18432
	ds_read_b128 v[188:191], v162 offset:19456
	ds_read_b128 v[192:195], v162 offset:20480
	ds_read_b128 v[196:199], v162 offset:21504
	ds_read_b128 v[200:203], v162 offset:22528
	ds_read_b128 v[204:207], v162 offset:23552
	s_add_i32 s20, s20, s5
	v_lshl_add_u64 v[130:131], s[14:15], 0, v[128:129]
	s_mov_b32 m0, s20
	v_lshl_add_u64 v[132:133], s[14:15], 0, v[148:149]
	global_load_lds_dwordx4 v[130:131], off
	s_add_i32 m0, s20, 0x2000
	s_nop 0
	global_load_lds_dwordx4 v[132:133], off
	s_mov_b32 m0, s9
	v_lshl_add_u64 v[134:135], s[18:19], 0, v[144:145]
	global_load_lds_dwordx4 v[134:135], off
	v_lshl_add_u64 v[136:137], s[18:19], 0, v[146:147]
	s_mov_b32 m0, s36
	s_nop 0
	global_load_lds_dwordx4 v[136:137], off
	s_add_u32 s48, s14, 0x40000
	s_addc_u32 s49, s15, 0
	s_add_i32 s20, s35, s5
	v_lshl_add_u64 v[138:139], s[48:49], 0, v[128:129]
	s_mov_b32 m0, s20
	s_nop 0
	global_load_lds_dwordx4 v[138:139], off
	v_lshl_add_u64 v[138:139], s[48:49], 0, v[148:149]
	s_add_i32 m0, s20, 0x2000
	s_nop 0
	global_load_lds_dwordx4 v[138:139], off
	s_waitcnt vmcnt(8) lgkmcnt(0)
	s_barrier
	v_mfma_f32_16x16x32_bf16 v[60:63], v[154:157], v[176:179], v[60:63]
	v_mfma_f32_16x16x32_bf16 v[56:59], v[168:171], v[176:179], v[56:59]
	v_mfma_f32_16x16x32_bf16 v[44:47], v[154:157], v[184:187], v[44:47]
	v_mfma_f32_16x16x32_bf16 v[40:43], v[168:171], v[184:187], v[40:43]
	v_mfma_f32_16x16x32_bf16 v[28:31], v[154:157], v[192:195], v[28:31]
	v_mfma_f32_16x16x32_bf16 v[24:27], v[168:171], v[192:195], v[24:27]
	v_mfma_f32_16x16x32_bf16 v[12:15], v[154:157], v[200:203], v[12:15]
	v_mfma_f32_16x16x32_bf16 v[8:11], v[168:171], v[200:203], v[8:11]
	v_mfma_f32_16x16x32_bf16 v[60:63], v[164:167], v[180:183], v[60:63]
	v_mfma_f32_16x16x32_bf16 v[56:59], v[172:175], v[180:183], v[56:59]
	v_mfma_f32_16x16x32_bf16 v[44:47], v[164:167], v[188:191], v[44:47]
	v_mfma_f32_16x16x32_bf16 v[40:43], v[172:175], v[188:191], v[40:43]
	v_mfma_f32_16x16x32_bf16 v[28:31], v[164:167], v[196:199], v[28:31]
	v_mfma_f32_16x16x32_bf16 v[24:27], v[172:175], v[196:199], v[24:27]
	v_mfma_f32_16x16x32_bf16 v[12:15], v[164:167], v[204:207], v[12:15]
	v_mfma_f32_16x16x32_bf16 v[8:11], v[172:175], v[204:207], v[8:11]
	v_mfma_f32_16x16x32_bf16 v[52:55], v[208:211], v[176:179], v[52:55]
	v_mfma_f32_16x16x32_bf16 v[48:51], v[216:219], v[176:179], v[48:51]
	v_mfma_f32_16x16x32_bf16 v[36:39], v[208:211], v[184:187], v[36:39]
	v_mfma_f32_16x16x32_bf16 v[32:35], v[216:219], v[184:187], v[32:35]
	v_mfma_f32_16x16x32_bf16 v[20:23], v[208:211], v[192:195], v[20:23]
	v_mfma_f32_16x16x32_bf16 v[16:19], v[216:219], v[192:195], v[16:19]
	v_mfma_f32_16x16x32_bf16 v[4:7], v[208:211], v[200:203], v[4:7]
	v_mfma_f32_16x16x32_bf16 v[0:3], v[216:219], v[200:203], v[0:3]
	v_mfma_f32_16x16x32_bf16 v[52:55], v[212:215], v[180:183], v[52:55]
	v_mfma_f32_16x16x32_bf16 v[48:51], v[220:223], v[180:183], v[48:51]
	v_mfma_f32_16x16x32_bf16 v[36:39], v[212:215], v[188:191], v[36:39]
	v_mfma_f32_16x16x32_bf16 v[32:35], v[220:223], v[188:191], v[32:35]
	v_mfma_f32_16x16x32_bf16 v[20:23], v[212:215], v[196:199], v[20:23]
	v_mfma_f32_16x16x32_bf16 v[16:19], v[220:223], v[196:199], v[16:19]
	v_mfma_f32_16x16x32_bf16 v[4:7], v[212:215], v[204:207], v[4:7]
	v_mfma_f32_16x16x32_bf16 v[0:3], v[220:223], v[204:207], v[0:3]
	s_add_i32 s20, 16, 0x18000
	v_add_u32_e32 v138, s20, v160
	s_barrier
	ds_read_b128 v[154:157], v138
	ds_read_b128 v[164:167], v138 offset:1024
	ds_read_b128 v[168:171], v138 offset:2048
	ds_read_b128 v[172:175], v138 offset:3072
	s_add_u32 s18, s18, 0x40000
	s_addc_u32 s19, s19, 0
	s_mov_b32 m0, s37
	v_lshl_add_u64 v[158:159], s[18:19], 0, v[144:145]
	ds_read_b128 v[176:179], v162 offset:32768
	ds_read_b128 v[180:183], v162 offset:33792
	ds_read_b128 v[184:187], v162 offset:34816
	ds_read_b128 v[188:191], v162 offset:35840
	ds_read_b128 v[192:195], v162 offset:36864
	ds_read_b128 v[196:199], v162 offset:37888
	ds_read_b128 v[200:203], v162 offset:38912
	ds_read_b128 v[204:207], v162 offset:39936
	global_load_lds_dwordx4 v[158:159], off
	v_lshl_add_u64 v[158:159], s[18:19], 0, v[146:147]
	s_mov_b32 m0, s46
	s_nop 0
	global_load_lds_dwordx4 v[158:159], off
	s_add_i32 s18, 16, 0x1c000
	v_add_u32_e32 v138, s18, v160
	ds_read_b128 v[208:211], v138
	ds_read_b128 v[212:215], v138 offset:1024
	ds_read_b128 v[216:219], v138 offset:2048
	ds_read_b128 v[220:223], v138 offset:3072
	s_waitcnt vmcnt(8) lgkmcnt(0)
	s_barrier
	v_mfma_f32_16x16x32_bf16 v[124:127], v[154:157], v[176:179], v[124:127]
	v_mfma_f32_16x16x32_bf16 v[120:123], v[168:171], v[176:179], v[120:123]
	v_mfma_f32_16x16x32_bf16 v[108:111], v[154:157], v[184:187], v[108:111]
	v_mfma_f32_16x16x32_bf16 v[104:107], v[168:171], v[184:187], v[104:107]
	v_mfma_f32_16x16x32_bf16 v[92:95], v[154:157], v[192:195], v[92:95]
	v_mfma_f32_16x16x32_bf16 v[88:91], v[168:171], v[192:195], v[88:91]
	v_mfma_f32_16x16x32_bf16 v[76:79], v[154:157], v[200:203], v[76:79]
	v_mfma_f32_16x16x32_bf16 v[72:75], v[168:171], v[200:203], v[72:75]
	v_mfma_f32_16x16x32_bf16 v[124:127], v[164:167], v[180:183], v[124:127]
	v_mfma_f32_16x16x32_bf16 v[120:123], v[172:175], v[180:183], v[120:123]
	v_mfma_f32_16x16x32_bf16 v[108:111], v[164:167], v[188:191], v[108:111]
	v_mfma_f32_16x16x32_bf16 v[104:107], v[172:175], v[188:191], v[104:107]
	v_mfma_f32_16x16x32_bf16 v[92:95], v[164:167], v[196:199], v[92:95]
	v_mfma_f32_16x16x32_bf16 v[88:91], v[172:175], v[196:199], v[88:91]
	v_mfma_f32_16x16x32_bf16 v[76:79], v[164:167], v[204:207], v[76:79]
	v_mfma_f32_16x16x32_bf16 v[72:75], v[172:175], v[204:207], v[72:75]
	v_mfma_f32_16x16x32_bf16 v[116:119], v[208:211], v[176:179], v[116:119]
	v_mfma_f32_16x16x32_bf16 v[112:115], v[216:219], v[176:179], v[112:115]
	v_mfma_f32_16x16x32_bf16 v[100:103], v[208:211], v[184:187], v[100:103]
	v_mfma_f32_16x16x32_bf16 v[96:99], v[216:219], v[184:187], v[96:99]
	v_mfma_f32_16x16x32_bf16 v[84:87], v[208:211], v[192:195], v[84:87]
	v_mfma_f32_16x16x32_bf16 v[80:83], v[216:219], v[192:195], v[80:83]
	v_mfma_f32_16x16x32_bf16 v[68:71], v[208:211], v[200:203], v[68:71]
	v_mfma_f32_16x16x32_bf16 v[64:67], v[216:219], v[200:203], v[64:67]
	v_mfma_f32_16x16x32_bf16 v[116:119], v[212:215], v[180:183], v[116:119]
	v_mfma_f32_16x16x32_bf16 v[112:115], v[220:223], v[180:183], v[112:115]
	v_mfma_f32_16x16x32_bf16 v[100:103], v[212:215], v[188:191], v[100:103]
	v_mfma_f32_16x16x32_bf16 v[96:99], v[220:223], v[188:191], v[96:99]
	v_mfma_f32_16x16x32_bf16 v[84:87], v[212:215], v[196:199], v[84:87]
	v_mfma_f32_16x16x32_bf16 v[80:83], v[220:223], v[196:199], v[80:83]
	v_mfma_f32_16x16x32_bf16 v[68:71], v[212:215], v[204:207], v[68:71]
	v_mfma_f32_16x16x32_bf16 v[64:67], v[220:223], v[204:207], v[64:67]
	s_barrier
	ds_read_b128 v[176:179], v162 offset:49152
	ds_read_b128 v[180:183], v162 offset:50176
	ds_read_b128 v[184:187], v162 offset:51200
	ds_read_b128 v[188:191], v162 offset:52224
	ds_read_b128 v[192:195], v162 offset:53248
	ds_read_b128 v[196:199], v162 offset:54272
	ds_read_b128 v[200:203], v162 offset:55296
	ds_read_b128 v[204:207], v162 offset:56320
	s_add_i32 s19, s20, s5
	v_lshl_add_u64 v[130:131], v[130:131], 0, s[28:29]
	s_mov_b32 m0, s19
	s_nop 0
	global_load_lds_dwordx4 v[130:131], off
	v_lshl_add_u64 v[130:131], v[132:133], 0, s[28:29]
	s_add_i32 m0, s19, 0x2000
	s_nop 0
	global_load_lds_dwordx4 v[130:131], off
	s_mov_b32 m0, s47
	v_lshl_add_u64 v[130:131], v[134:135], 0, s[28:29]
	global_load_lds_dwordx4 v[130:131], off
	v_lshl_add_u64 v[130:131], v[136:137], 0, s[28:29]
	s_mov_b32 m0, s92
	s_nop 0
	global_load_lds_dwordx4 v[130:131], off
	s_add_u32 s14, s14, 0x40080
	s_addc_u32 s15, s15, 0
	s_add_i32 s18, s18, s5
	v_lshl_add_u64 v[130:131], s[14:15], 0, v[128:129]
	s_mov_b32 m0, s18
	s_nop 0
	global_load_lds_dwordx4 v[130:131], off
	v_lshl_add_u64 v[130:131], s[14:15], 0, v[148:149]
	s_add_i32 m0, s18, 0x2000
	s_nop 0
	global_load_lds_dwordx4 v[130:131], off
	s_waitcnt vmcnt(8) lgkmcnt(0)
	s_barrier
	v_mfma_f32_16x16x32_bf16 v[60:63], v[154:157], v[176:179], v[60:63]
	v_mfma_f32_16x16x32_bf16 v[56:59], v[168:171], v[176:179], v[56:59]
	v_mfma_f32_16x16x32_bf16 v[44:47], v[154:157], v[184:187], v[44:47]
	v_mfma_f32_16x16x32_bf16 v[40:43], v[168:171], v[184:187], v[40:43]
	v_mfma_f32_16x16x32_bf16 v[28:31], v[154:157], v[192:195], v[28:31]
	v_mfma_f32_16x16x32_bf16 v[24:27], v[168:171], v[192:195], v[24:27]
	v_mfma_f32_16x16x32_bf16 v[12:15], v[154:157], v[200:203], v[12:15]
	v_mfma_f32_16x16x32_bf16 v[8:11], v[168:171], v[200:203], v[8:11]
	v_mfma_f32_16x16x32_bf16 v[60:63], v[164:167], v[180:183], v[60:63]
	v_mfma_f32_16x16x32_bf16 v[56:59], v[172:175], v[180:183], v[56:59]
	v_mfma_f32_16x16x32_bf16 v[44:47], v[164:167], v[188:191], v[44:47]
	v_mfma_f32_16x16x32_bf16 v[40:43], v[172:175], v[188:191], v[40:43]
	v_mfma_f32_16x16x32_bf16 v[28:31], v[164:167], v[196:199], v[28:31]
	v_mfma_f32_16x16x32_bf16 v[24:27], v[172:175], v[196:199], v[24:27]
	v_mfma_f32_16x16x32_bf16 v[12:15], v[164:167], v[204:207], v[12:15]
	v_mfma_f32_16x16x32_bf16 v[8:11], v[172:175], v[204:207], v[8:11]
	v_mfma_f32_16x16x32_bf16 v[52:55], v[208:211], v[176:179], v[52:55]
	v_mfma_f32_16x16x32_bf16 v[48:51], v[216:219], v[176:179], v[48:51]
	v_mfma_f32_16x16x32_bf16 v[36:39], v[208:211], v[184:187], v[36:39]
	v_mfma_f32_16x16x32_bf16 v[32:35], v[216:219], v[184:187], v[32:35]
	v_mfma_f32_16x16x32_bf16 v[20:23], v[208:211], v[192:195], v[20:23]
	v_mfma_f32_16x16x32_bf16 v[16:19], v[216:219], v[192:195], v[16:19]
	v_mfma_f32_16x16x32_bf16 v[4:7], v[208:211], v[200:203], v[4:7]
	v_mfma_f32_16x16x32_bf16 v[0:3], v[216:219], v[200:203], v[0:3]
	v_mfma_f32_16x16x32_bf16 v[52:55], v[212:215], v[180:183], v[52:55]
	v_mfma_f32_16x16x32_bf16 v[48:51], v[220:223], v[180:183], v[48:51]
	v_mfma_f32_16x16x32_bf16 v[36:39], v[212:215], v[188:191], v[36:39]
	v_mfma_f32_16x16x32_bf16 v[32:35], v[220:223], v[188:191], v[32:35]
	v_mfma_f32_16x16x32_bf16 v[20:23], v[212:215], v[196:199], v[20:23]
	v_mfma_f32_16x16x32_bf16 v[16:19], v[220:223], v[196:199], v[16:19]
	v_mfma_f32_16x16x32_bf16 v[4:7], v[212:215], v[204:207], v[4:7]
	v_mfma_f32_16x16x32_bf16 v[0:3], v[220:223], v[204:207], v[0:3]
	s_add_i32 s34, s34, 2
	s_add_u32 vcc_lo, vcc_lo, 0x100
	s_addc_u32 vcc_hi, vcc_hi, 0
	s_add_u32 s25, s25, 0x100
	s_addc_u32 s31, s31, 0
	s_cmp_gt_u32 s34, 13
	s_cbranch_scc1 .Lgout_exit
	s_barrier
	s_branch .LBB0_128

.Lgout_epi:
	s_nop 0
	s_nop 0
	s_nop 0
	s_nop 0
	s_nop 0
	s_nop 0
	s_nop 0
	s_nop 0
	s_cmp_lt_i32 s8, 0
	s_cselect_b64 s[14:15], -1, 0
	s_cmp_gt_i32 s8, -1
	s_cbranch_scc1 .LBB0_131
	v_mul_f32_e32 v131, 0x3d372713, v120
	v_mul_f32_e32 v131, v120, v131
	v_fma_f32 v131, v120, v131, v120
	v_mul_f32_e32 v131, 0x3fcc422a, v131
	v_mul_f32_e32 v131, 0xbfb8aa3b, v131
	v_exp_f32_e32 v131, v131
	v_mul_f32_e32 v130, 0x3d372713, v124
	v_mul_f32_e32 v130, v124, v130
	v_fma_f32 v130, v124, v130, v124
	v_add_f32_e32 v131, 1.0, v131
	v_rcp_f32_e32 v132, v131
	v_mul_f32_e32 v131, 0x3d372713, v125
	v_mul_f32_e32 v131, v125, v131
	v_fma_f32 v131, v125, v131, v125
	v_mul_f32_e32 v130, 0x3fcc422a, v130
	v_mul_f32_e32 v131, 0x3fcc422a, v131
	v_mul_f32_e32 v130, 0xbfb8aa3b, v130
	v_mul_f32_e32 v131, 0xbfb8aa3b, v131
	v_mul_f32_e32 v135, 0x3d372713, v122
	v_exp_f32_e32 v130, v130
	v_exp_f32_e32 v131, v131
	v_mul_f32_e32 v135, v122, v135
	v_fma_f32 v135, v122, v135, v122
	v_mul_f32_e32 v135, 0x3fcc422a, v135
	v_mul_f32_e32 v135, 0xbfb8aa3b, v135
	v_add_f32_e32 v130, 1.0, v130
	v_add_f32_e32 v131, 1.0, v131
	v_exp_f32_e32 v135, v135
	v_rcp_f32_e32 v130, v130
	v_rcp_f32_e32 v131, v131
	v_mul_f32_e32 v133, 0x3d372713, v121
	v_add_f32_e32 v135, 1.0, v135
	v_mul_f32_e32 v134, 0x3d372713, v126
	v_rcp_f32_e32 v136, v135
	v_mul_f32_e32 v135, 0x3d372713, v127
	v_pk_mul_f32 v[124:125], v[124:125], v[130:131]
	v_mul_f32_e32 v130, 0x3d372713, v123
	v_mul_f32_e32 v133, v121, v133
	v_mul_f32_e32 v134, v126, v134
	v_mul_f32_e32 v135, v127, v135
	v_mul_f32_e32 v130, v123, v130
	v_fma_f32 v133, v121, v133, v121
	v_fma_f32 v134, v126, v134, v126
	v_fma_f32 v135, v127, v135, v127
	v_fma_f32 v130, v123, v130, v123
	v_mul_f32_e32 v133, 0x3fcc422a, v133
	v_mul_f32_e32 v134, 0x3fcc422a, v134
	v_mul_f32_e32 v135, 0x3fcc422a, v135
	v_mul_f32_e32 v130, 0x3fcc422a, v130
	v_mul_f32_e32 v133, 0xbfb8aa3b, v133
	v_mul_f32_e32 v134, 0xbfb8aa3b, v134
	v_mul_f32_e32 v135, 0xbfb8aa3b, v135
	v_mul_f32_e32 v130, 0xbfb8aa3b, v130
	v_exp_f32_e32 v133, v133
	v_exp_f32_e32 v134, v134
	v_exp_f32_e32 v135, v135
	v_exp_f32_e32 v130, v130
	v_add_f32_e32 v133, 1.0, v133
	v_add_f32_e32 v134, 1.0, v134
	v_add_f32_e32 v135, 1.0, v135
	v_add_f32_e32 v130, 1.0, v130
	v_rcp_f32_e32 v133, v133
	v_rcp_f32_e32 v134, v134
	v_rcp_f32_e32 v135, v135
	v_rcp_f32_e32 v137, v130
	v_pk_mul_f32 v[120:121], v[120:121], v[132:133]
	v_pk_mul_f32 v[126:127], v[126:127], v[134:135]
	v_pk_mul_f32 v[122:123], v[122:123], v[136:137]

.LBB0_270:
	v_lshl_add_u32 v154, s14, 8, v143
	v_readlane_b32 s14, v252, 43
	v_mov_b64_e32 v[0:1], 0x600
	v_ashrrev_i32_e32 v155, 31, v154
	v_readlane_b32 s15, v252, 44
	v_cmp_lt_i64_e32 vcc, s[34:35], v[0:1]
	s_ashr_i32 s13, s12, 31
	v_lshl_add_u64 v[0:1], v[154:155], 2, s[14:15]
	global_load_dword v156, v[0:1], off
	global_load_dword v171, v[0:1], off offset:64
	global_load_dword v170, v[0:1], off offset:128
	global_load_dword v169, v[0:1], off offset:192
	global_load_dword v168, v[0:1], off offset:512
	global_load_dword v167, v[0:1], off offset:576
	global_load_dword v166, v[0:1], off offset:640
	global_load_dword v165, v[0:1], off offset:704
	s_lshl_b64 s[0:1], s[12:13], 19
	v_readlane_b32 s24, v252, 55
	v_readlane_b32 s25, v252, 56
	s_add_u32 s42, s24, s0
	s_addc_u32 s43, s25, s1
	s_and_b64 s[0:1], vcc, exec
	s_cselect_b32 s0, s43, s31
	s_cselect_b32 s1, s42, s30
	s_ashr_i32 s9, s8, 31
	s_lshl_b64 s[24:25], s[8:9], 19
	v_readlane_b32 s34, v252, 41
	v_readlane_b32 s35, v252, 42
	s_add_u32 s44, s34, s24
	s_addc_u32 s45, s35, s25
	s_and_b64 s[24:25], vcc, exec
	s_cselect_b32 s9, s45, s19
	s_cselect_b32 s13, s44, s18
	s_add_u32 s30, s30, 0x40080
	s_addc_u32 s31, s31, 0
	s_add_u32 s17, s18, 0x100
	v_mov_b32_e32 v0, 0
	s_addc_u32 s24, s19, 0
	s_mov_b32 s25, -2
	v_mov_b32_e32 v1, v0
	v_mov_b32_e32 v2, v0
	v_mov_b32_e32 v3, v0
	v_mov_b32_e32 v4, v0
	v_mov_b32_e32 v5, v0
	v_mov_b32_e32 v6, v0
	v_mov_b32_e32 v7, v0
	v_mov_b32_e32 v16, v0
	v_mov_b32_e32 v17, v0
	v_mov_b32_e32 v18, v0
	v_mov_b32_e32 v19, v0
	v_mov_b32_e32 v20, v0
	v_mov_b32_e32 v21, v0
	v_mov_b32_e32 v22, v0
	v_mov_b32_e32 v23, v0
	v_mov_b32_e32 v32, v0
	v_mov_b32_e32 v33, v0
	v_mov_b32_e32 v34, v0
	v_mov_b32_e32 v35, v0
	v_mov_b32_e32 v36, v0
	v_mov_b32_e32 v37, v0
	v_mov_b32_e32 v38, v0
	v_mov_b32_e32 v39, v0
	v_mov_b32_e32 v48, v0
	v_mov_b32_e32 v49, v0
	v_mov_b32_e32 v50, v0
	v_mov_b32_e32 v51, v0
	v_mov_b32_e32 v52, v0
	v_mov_b32_e32 v53, v0
	v_mov_b32_e32 v54, v0
	v_mov_b32_e32 v55, v0
	v_mov_b32_e32 v8, v0
	v_mov_b32_e32 v9, v0
	v_mov_b32_e32 v10, v0
	v_mov_b32_e32 v11, v0
	v_mov_b32_e32 v12, v0
	v_mov_b32_e32 v13, v0
	v_mov_b32_e32 v14, v0
	v_mov_b32_e32 v15, v0
	v_mov_b32_e32 v24, v0
	v_mov_b32_e32 v25, v0
	v_mov_b32_e32 v26, v0
	v_mov_b32_e32 v27, v0
	v_mov_b32_e32 v28, v0
	v_mov_b32_e32 v29, v0
	v_mov_b32_e32 v30, v0
	v_mov_b32_e32 v31, v0
	v_mov_b32_e32 v40, v0
	v_mov_b32_e32 v41, v0
	v_mov_b32_e32 v42, v0
	v_mov_b32_e32 v43, v0
	v_mov_b32_e32 v44, v0
	v_mov_b32_e32 v45, v0
	v_mov_b32_e32 v46, v0
	v_mov_b32_e32 v47, v0
	v_mov_b32_e32 v56, v0
	v_mov_b32_e32 v57, v0
	v_mov_b32_e32 v58, v0
	v_mov_b32_e32 v59, v0
	v_mov_b32_e32 v60, v0
	v_mov_b32_e32 v61, v0
	v_mov_b32_e32 v62, v0
	v_mov_b32_e32 v63, v0
	v_mov_b32_e32 v64, v0
	v_mov_b32_e32 v65, v0
	v_mov_b32_e32 v66, v0
	v_mov_b32_e32 v67, v0
	v_mov_b32_e32 v68, v0
	v_mov_b32_e32 v69, v0
	v_mov_b32_e32 v70, v0
	v_mov_b32_e32 v71, v0
	v_mov_b32_e32 v80, v0
	v_mov_b32_e32 v81, v0
	v_mov_b32_e32 v82, v0
	v_mov_b32_e32 v83, v0
	v_mov_b32_e32 v84, v0
	v_mov_b32_e32 v85, v0
	v_mov_b32_e32 v86, v0
	v_mov_b32_e32 v87, v0
	v_mov_b32_e32 v96, v0
	v_mov_b32_e32 v97, v0
	v_mov_b32_e32 v98, v0
	v_mov_b32_e32 v99, v0
	v_mov_b32_e32 v100, v0
	v_mov_b32_e32 v101, v0
	v_mov_b32_e32 v102, v0
	v_mov_b32_e32 v103, v0
	v_mov_b32_e32 v112, v0
	v_mov_b32_e32 v113, v0
	v_mov_b32_e32 v114, v0
	v_mov_b32_e32 v115, v0
	v_mov_b32_e32 v116, v0
	v_mov_b32_e32 v117, v0
	v_mov_b32_e32 v118, v0
	v_mov_b32_e32 v119, v0
	v_mov_b32_e32 v72, v0
	v_mov_b32_e32 v73, v0
	v_mov_b32_e32 v74, v0
	v_mov_b32_e32 v75, v0
	v_mov_b32_e32 v76, v0
	v_mov_b32_e32 v77, v0
	v_mov_b32_e32 v78, v0
	v_mov_b32_e32 v79, v0
	v_mov_b32_e32 v88, v0
	v_mov_b32_e32 v89, v0
	v_mov_b32_e32 v90, v0
	v_mov_b32_e32 v91, v0
	v_mov_b32_e32 v92, v0
	v_mov_b32_e32 v93, v0
	v_mov_b32_e32 v94, v0
	v_mov_b32_e32 v95, v0
	v_mov_b32_e32 v104, v0
	v_mov_b32_e32 v105, v0
	v_mov_b32_e32 v106, v0
	v_mov_b32_e32 v107, v0
	v_mov_b32_e32 v108, v0
	v_mov_b32_e32 v109, v0
	v_mov_b32_e32 v110, v0
	v_mov_b32_e32 v111, v0
	v_mov_b32_e32 v120, v0
	v_mov_b32_e32 v121, v0
	v_mov_b32_e32 v122, v0
	v_mov_b32_e32 v123, v0
	v_mov_b32_e32 v124, v0
	v_mov_b32_e32 v125, v0
	v_mov_b32_e32 v126, v0
	v_mov_b32_e32 v127, v0
	s_cmpk_gt_u32 s48, 0xff
	s_cbranch_scc0 .Lgin_enter
	s_barrier
.Lgin_enter:
.LBB0_271:
	s_add_u32 s14, s30, 0xfffc0080
	s_addc_u32 s15, s31, -1
	s_add_i32 s20, 16, 0x10000
	v_add_u32_e32 v130, s20, v162
	ds_read_b128 v[158:161], v130
	ds_read_b128 v[172:175], v130 offset:1024
	ds_read_b128 v[176:179], v130 offset:2048
	ds_read_b128 v[180:183], v130 offset:3072
	s_cmp_eq_u32 s25, 12
	s_cselect_b32 s19, s0, s15
	s_cselect_b32 s18, s1, s14
	s_cselect_b32 s15, s9, s24
	s_cselect_b32 s14, s13, s17
	v_lshl_add_u64 v[130:131], s[30:31], 0, v[150:151]
	s_add_i32 m0, s5, 0xc000
	ds_read_b128 v[184:187], v164
	ds_read_b128 v[188:191], v164 offset:1024
	ds_read_b128 v[192:195], v164 offset:2048
	ds_read_b128 v[196:199], v164 offset:3072
	ds_read_b128 v[200:203], v164 offset:4096
	ds_read_b128 v[204:207], v164 offset:5120
	ds_read_b128 v[208:211], v164 offset:6144
	ds_read_b128 v[212:215], v164 offset:7168
	global_load_lds_dwordx4 v[130:131], off
	v_lshl_add_u64 v[130:131], s[30:31], 0, v[152:153]
	s_add_i32 m0, s5, 0xe000
	s_nop 0
	global_load_lds_dwordx4 v[130:131], off
	s_add_i32 s41, 16, 0x14000
	v_add_u32_e32 v130, s41, v162
	ds_read_b128 v[216:219], v130
	ds_read_b128 v[220:223], v130 offset:1024
	ds_read_b128 v[224:227], v130 offset:2048
	ds_read_b128 v[228:231], v130 offset:3072
	s_waitcnt vmcnt(8) lgkmcnt(0)
	s_barrier
	v_mfma_f32_16x16x32_bf16 v[124:127], v[158:161], v[184:187], v[124:127]
	v_mfma_f32_16x16x32_bf16 v[120:123], v[176:179], v[184:187], v[120:123]
	v_mfma_f32_16x16x32_bf16 v[108:111], v[158:161], v[192:195], v[108:111]
	v_mfma_f32_16x16x32_bf16 v[104:107], v[176:179], v[192:195], v[104:107]
	v_mfma_f32_16x16x32_bf16 v[92:95], v[158:161], v[200:203], v[92:95]
	v_mfma_f32_16x16x32_bf16 v[88:91], v[176:179], v[200:203], v[88:91]
	v_mfma_f32_16x16x32_bf16 v[76:79], v[158:161], v[208:211], v[76:79]
	v_mfma_f32_16x16x32_bf16 v[72:75], v[176:179], v[208:211], v[72:75]
	v_mfma_f32_16x16x32_bf16 v[124:127], v[172:175], v[188:191], v[124:127]
	v_mfma_f32_16x16x32_bf16 v[120:123], v[180:183], v[188:191], v[120:123]
	v_mfma_f32_16x16x32_bf16 v[108:111], v[172:175], v[196:199], v[108:111]
	v_mfma_f32_16x16x32_bf16 v[104:107], v[180:183], v[196:199], v[104:107]
	v_mfma_f32_16x16x32_bf16 v[92:95], v[172:175], v[204:207], v[92:95]
	v_mfma_f32_16x16x32_bf16 v[88:91], v[180:183], v[204:207], v[88:91]
	v_mfma_f32_16x16x32_bf16 v[76:79], v[172:175], v[212:215], v[76:79]
	v_mfma_f32_16x16x32_bf16 v[72:75], v[180:183], v[212:215], v[72:75]
	v_mfma_f32_16x16x32_bf16 v[116:119], v[216:219], v[184:187], v[116:119]
	v_mfma_f32_16x16x32_bf16 v[112:115], v[224:227], v[184:187], v[112:115]
	v_mfma_f32_16x16x32_bf16 v[100:103], v[216:219], v[192:195], v[100:103]
	v_mfma_f32_16x16x32_bf16 v[96:99], v[224:227], v[192:195], v[96:99]
	v_mfma_f32_16x16x32_bf16 v[84:87], v[216:219], v[200:203], v[84:87]
	v_mfma_f32_16x16x32_bf16 v[80:83], v[224:227], v[200:203], v[80:83]
	v_mfma_f32_16x16x32_bf16 v[68:71], v[216:219], v[208:211], v[68:71]
	v_mfma_f32_16x16x32_bf16 v[64:67], v[224:227], v[208:211], v[64:67]
	v_mfma_f32_16x16x32_bf16 v[116:119], v[220:223], v[188:191], v[116:119]
	v_mfma_f32_16x16x32_bf16 v[112:115], v[228:231], v[188:191], v[112:115]
	v_mfma_f32_16x16x32_bf16 v[100:103], v[220:223], v[196:199], v[100:103]
	v_mfma_f32_16x16x32_bf16 v[96:99], v[228:231], v[196:199], v[96:99]
	v_mfma_f32_16x16x32_bf16 v[84:87], v[220:223], v[204:207], v[84:87]
	v_mfma_f32_16x16x32_bf16 v[80:83], v[228:231], v[204:207], v[80:83]
	v_mfma_f32_16x16x32_bf16 v[68:71], v[220:223], v[212:215], v[68:71]
	v_mfma_f32_16x16x32_bf16 v[64:67], v[228:231], v[212:215], v[64:67]
	s_barrier
	ds_read_b128 v[184:187], v164 offset:16384
	ds_read_b128 v[188:191], v164 offset:17408
	ds_read_b128 v[192:195], v164 offset:18432
	ds_read_b128 v[196:199], v164 offset:19456
	ds_read_b128 v[200:203], v164 offset:20480
	ds_read_b128 v[204:207], v164 offset:21504
	ds_read_b128 v[208:211], v164 offset:22528
	ds_read_b128 v[212:215], v164 offset:23552
	s_add_i32 s20, s20, s92
	v_lshl_add_u64 v[130:131], s[14:15], 0, v[128:129]
	s_mov_b32 m0, s20
	v_lshl_add_u64 v[132:133], s[14:15], 0, v[148:149]
	global_load_lds_dwordx4 v[130:131], off
	s_add_i32 m0, s20, 0x2000
	s_nop 0
	global_load_lds_dwordx4 v[132:133], off
	s_mov_b32 m0, s5
	v_lshl_add_u64 v[134:135], s[18:19], 0, v[144:145]
	global_load_lds_dwordx4 v[134:135], off
	v_lshl_add_u64 v[136:137], s[18:19], 0, v[146:147]
	s_mov_b32 m0, s4
	s_nop 0
	global_load_lds_dwordx4 v[136:137], off
	s_add_u32 s34, s14, 0x40000
	s_addc_u32 s35, s15, 0
	s_add_i32 s20, s41, s92
	v_lshl_add_u64 v[138:139], s[34:35], 0, v[128:129]
	s_mov_b32 m0, s20
	s_nop 0
	global_load_lds_dwordx4 v[138:139], off
	v_lshl_add_u64 v[138:139], s[34:35], 0, v[148:149]
	s_add_i32 m0, s20, 0x2000
	s_nop 0
	global_load_lds_dwordx4 v[138:139], off
	s_waitcnt vmcnt(8) lgkmcnt(0)
	s_barrier
	v_mfma_f32_16x16x32_bf16 v[60:63], v[158:161], v[184:187], v[60:63]
	v_mfma_f32_16x16x32_bf16 v[56:59], v[176:179], v[184:187], v[56:59]
	v_mfma_f32_16x16x32_bf16 v[44:47], v[158:161], v[192:195], v[44:47]
	v_mfma_f32_16x16x32_bf16 v[40:43], v[176:179], v[192:195], v[40:43]
	v_mfma_f32_16x16x32_bf16 v[28:31], v[158:161], v[200:203], v[28:31]
	v_mfma_f32_16x16x32_bf16 v[24:27], v[176:179], v[200:203], v[24:27]
	v_mfma_f32_16x16x32_bf16 v[12:15], v[158:161], v[208:211], v[12:15]
	v_mfma_f32_16x16x32_bf16 v[8:11], v[176:179], v[208:211], v[8:11]
	v_mfma_f32_16x16x32_bf16 v[60:63], v[172:175], v[188:191], v[60:63]
	v_mfma_f32_16x16x32_bf16 v[56:59], v[180:183], v[188:191], v[56:59]
	v_mfma_f32_16x16x32_bf16 v[44:47], v[172:175], v[196:199], v[44:47]
	v_mfma_f32_16x16x32_bf16 v[40:43], v[180:183], v[196:199], v[40:43]
	v_mfma_f32_16x16x32_bf16 v[28:31], v[172:175], v[204:207], v[28:31]
	v_mfma_f32_16x16x32_bf16 v[24:27], v[180:183], v[204:207], v[24:27]
	v_mfma_f32_16x16x32_bf16 v[12:15], v[172:175], v[212:215], v[12:15]
	v_mfma_f32_16x16x32_bf16 v[8:11], v[180:183], v[212:215], v[8:11]
	v_mfma_f32_16x16x32_bf16 v[52:55], v[216:219], v[184:187], v[52:55]
	v_mfma_f32_16x16x32_bf16 v[48:51], v[224:227], v[184:187], v[48:51]
	v_mfma_f32_16x16x32_bf16 v[36:39], v[216:219], v[192:195], v[36:39]
	v_mfma_f32_16x16x32_bf16 v[32:35], v[224:227], v[192:195], v[32:35]
	v_mfma_f32_16x16x32_bf16 v[20:23], v[216:219], v[200:203], v[20:23]
	v_mfma_f32_16x16x32_bf16 v[16:19], v[224:227], v[200:203], v[16:19]
	v_mfma_f32_16x16x32_bf16 v[4:7], v[216:219], v[208:211], v[4:7]
	v_mfma_f32_16x16x32_bf16 v[0:3], v[224:227], v[208:211], v[0:3]
	v_mfma_f32_16x16x32_bf16 v[52:55], v[220:223], v[188:191], v[52:55]
	v_mfma_f32_16x16x32_bf16 v[48:51], v[228:231], v[188:191], v[48:51]
	v_mfma_f32_16x16x32_bf16 v[36:39], v[220:223], v[196:199], v[36:39]
	v_mfma_f32_16x16x32_bf16 v[32:35], v[228:231], v[196:199], v[32:35]
	v_mfma_f32_16x16x32_bf16 v[20:23], v[220:223], v[204:207], v[20:23]
	v_mfma_f32_16x16x32_bf16 v[16:19], v[228:231], v[204:207], v[16:19]
	v_mfma_f32_16x16x32_bf16 v[4:7], v[220:223], v[212:215], v[4:7]
	v_mfma_f32_16x16x32_bf16 v[0:3], v[228:231], v[212:215], v[0:3]
	s_add_i32 s20, 16, 0x18000
	v_add_u32_e32 v138, s20, v162
	s_barrier
	ds_read_b128 v[158:161], v138
	ds_read_b128 v[172:175], v138 offset:1024
	ds_read_b128 v[176:179], v138 offset:2048
	ds_read_b128 v[180:183], v138 offset:3072
	s_add_u32 s18, s18, 0x40000
	s_addc_u32 s19, s19, 0
	s_mov_b32 m0, s36
	v_lshl_add_u64 v[216:217], s[18:19], 0, v[144:145]
	ds_read_b128 v[184:187], v164 offset:32768
	ds_read_b128 v[188:191], v164 offset:33792
	ds_read_b128 v[192:195], v164 offset:34816
	ds_read_b128 v[196:199], v164 offset:35840
	ds_read_b128 v[200:203], v164 offset:36864
	ds_read_b128 v[204:207], v164 offset:37888
	ds_read_b128 v[208:211], v164 offset:38912
	ds_read_b128 v[212:215], v164 offset:39936
	global_load_lds_dwordx4 v[216:217], off
	v_lshl_add_u64 v[216:217], s[18:19], 0, v[146:147]
	s_mov_b32 m0, s37
	s_nop 0
	global_load_lds_dwordx4 v[216:217], off
	s_add_i32 s18, 16, 0x1c000
	v_add_u32_e32 v138, s18, v162
	ds_read_b128 v[216:219], v138
	ds_read_b128 v[220:223], v138 offset:1024
	ds_read_b128 v[224:227], v138 offset:2048
	ds_read_b128 v[228:231], v138 offset:3072
	s_waitcnt vmcnt(8) lgkmcnt(0)
	s_barrier
	v_mfma_f32_16x16x32_bf16 v[124:127], v[158:161], v[184:187], v[124:127]
	v_mfma_f32_16x16x32_bf16 v[120:123], v[176:179], v[184:187], v[120:123]
	v_mfma_f32_16x16x32_bf16 v[108:111], v[158:161], v[192:195], v[108:111]
	v_mfma_f32_16x16x32_bf16 v[104:107], v[176:179], v[192:195], v[104:107]
	v_mfma_f32_16x16x32_bf16 v[92:95], v[158:161], v[200:203], v[92:95]
	v_mfma_f32_16x16x32_bf16 v[88:91], v[176:179], v[200:203], v[88:91]
	v_mfma_f32_16x16x32_bf16 v[76:79], v[158:161], v[208:211], v[76:79]
	v_mfma_f32_16x16x32_bf16 v[72:75], v[176:179], v[208:211], v[72:75]
	v_mfma_f32_16x16x32_bf16 v[124:127], v[172:175], v[188:191], v[124:127]
	v_mfma_f32_16x16x32_bf16 v[120:123], v[180:183], v[188:191], v[120:123]
	v_mfma_f32_16x16x32_bf16 v[108:111], v[172:175], v[196:199], v[108:111]
	v_mfma_f32_16x16x32_bf16 v[104:107], v[180:183], v[196:199], v[104:107]
	v_mfma_f32_16x16x32_bf16 v[92:95], v[172:175], v[204:207], v[92:95]
	v_mfma_f32_16x16x32_bf16 v[88:91], v[180:183], v[204:207], v[88:91]
	v_mfma_f32_16x16x32_bf16 v[76:79], v[172:175], v[212:215], v[76:79]
	v_mfma_f32_16x16x32_bf16 v[72:75], v[180:183], v[212:215], v[72:75]
	v_mfma_f32_16x16x32_bf16 v[116:119], v[216:219], v[184:187], v[116:119]
	v_mfma_f32_16x16x32_bf16 v[112:115], v[224:227], v[184:187], v[112:115]
	v_mfma_f32_16x16x32_bf16 v[100:103], v[216:219], v[192:195], v[100:103]
	v_mfma_f32_16x16x32_bf16 v[96:99], v[224:227], v[192:195], v[96:99]
	v_mfma_f32_16x16x32_bf16 v[84:87], v[216:219], v[200:203], v[84:87]
	v_mfma_f32_16x16x32_bf16 v[80:83], v[224:227], v[200:203], v[80:83]
	v_mfma_f32_16x16x32_bf16 v[68:71], v[216:219], v[208:211], v[68:71]
	v_mfma_f32_16x16x32_bf16 v[64:67], v[224:227], v[208:211], v[64:67]
	v_mfma_f32_16x16x32_bf16 v[116:119], v[220:223], v[188:191], v[116:119]
	v_mfma_f32_16x16x32_bf16 v[112:115], v[228:231], v[188:191], v[112:115]
	v_mfma_f32_16x16x32_bf16 v[100:103], v[220:223], v[196:199], v[100:103]
	v_mfma_f32_16x16x32_bf16 v[96:99], v[228:231], v[196:199], v[96:99]
	v_mfma_f32_16x16x32_bf16 v[84:87], v[220:223], v[204:207], v[84:87]
	v_mfma_f32_16x16x32_bf16 v[80:83], v[228:231], v[204:207], v[80:83]
	v_mfma_f32_16x16x32_bf16 v[68:71], v[220:223], v[212:215], v[68:71]
	v_mfma_f32_16x16x32_bf16 v[64:67], v[228:231], v[212:215], v[64:67]
	s_barrier
	ds_read_b128 v[184:187], v164 offset:49152
	ds_read_b128 v[188:191], v164 offset:50176
	ds_read_b128 v[192:195], v164 offset:51200
	ds_read_b128 v[196:199], v164 offset:52224
	ds_read_b128 v[200:203], v164 offset:53248
	ds_read_b128 v[204:207], v164 offset:54272
	ds_read_b128 v[208:211], v164 offset:55296
	ds_read_b128 v[212:215], v164 offset:56320
	s_add_i32 s19, s20, s92
	v_lshl_add_u64 v[130:131], v[130:131], 0, s[28:29]
	s_mov_b32 m0, s19
	s_nop 0
	global_load_lds_dwordx4 v[130:131], off
	v_lshl_add_u64 v[130:131], v[132:133], 0, s[28:29]
	s_add_i32 m0, s19, 0x2000
	s_nop 0
	global_load_lds_dwordx4 v[130:131], off
	s_mov_b32 m0, s46
	v_lshl_add_u64 v[130:131], v[134:135], 0, s[28:29]
	global_load_lds_dwordx4 v[130:131], off
	v_lshl_add_u64 v[130:131], v[136:137], 0, s[28:29]
	s_mov_b32 m0, s47
	s_nop 0
	global_load_lds_dwordx4 v[130:131], off
	s_add_u32 s14, s14, 0x40080
	s_addc_u32 s15, s15, 0
	s_add_i32 s18, s18, s92
	v_lshl_add_u64 v[130:131], s[14:15], 0, v[128:129]
	s_mov_b32 m0, s18
	s_nop 0
	global_load_lds_dwordx4 v[130:131], off
	v_lshl_add_u64 v[130:131], s[14:15], 0, v[148:149]
	s_add_i32 m0, s18, 0x2000
	s_nop 0
	global_load_lds_dwordx4 v[130:131], off
	s_waitcnt vmcnt(8) lgkmcnt(0)
	s_barrier
	v_mfma_f32_16x16x32_bf16 v[60:63], v[158:161], v[184:187], v[60:63]
	v_mfma_f32_16x16x32_bf16 v[56:59], v[176:179], v[184:187], v[56:59]
	v_mfma_f32_16x16x32_bf16 v[44:47], v[158:161], v[192:195], v[44:47]
	v_mfma_f32_16x16x32_bf16 v[40:43], v[176:179], v[192:195], v[40:43]
	v_mfma_f32_16x16x32_bf16 v[28:31], v[158:161], v[200:203], v[28:31]
	v_mfma_f32_16x16x32_bf16 v[24:27], v[176:179], v[200:203], v[24:27]
	v_mfma_f32_16x16x32_bf16 v[12:15], v[158:161], v[208:211], v[12:15]
	v_mfma_f32_16x16x32_bf16 v[8:11], v[176:179], v[208:211], v[8:11]
	v_mfma_f32_16x16x32_bf16 v[60:63], v[172:175], v[188:191], v[60:63]
	v_mfma_f32_16x16x32_bf16 v[56:59], v[180:183], v[188:191], v[56:59]
	v_mfma_f32_16x16x32_bf16 v[44:47], v[172:175], v[196:199], v[44:47]
	v_mfma_f32_16x16x32_bf16 v[40:43], v[180:183], v[196:199], v[40:43]
	v_mfma_f32_16x16x32_bf16 v[28:31], v[172:175], v[204:207], v[28:31]
	v_mfma_f32_16x16x32_bf16 v[24:27], v[180:183], v[204:207], v[24:27]
	v_mfma_f32_16x16x32_bf16 v[12:15], v[172:175], v[212:215], v[12:15]
	v_mfma_f32_16x16x32_bf16 v[8:11], v[180:183], v[212:215], v[8:11]
	v_mfma_f32_16x16x32_bf16 v[52:55], v[216:219], v[184:187], v[52:55]
	v_mfma_f32_16x16x32_bf16 v[48:51], v[224:227], v[184:187], v[48:51]
	v_mfma_f32_16x16x32_bf16 v[36:39], v[216:219], v[192:195], v[36:39]
	v_mfma_f32_16x16x32_bf16 v[32:35], v[224:227], v[192:195], v[32:35]
	v_mfma_f32_16x16x32_bf16 v[20:23], v[216:219], v[200:203], v[20:23]
	v_mfma_f32_16x16x32_bf16 v[16:19], v[224:227], v[200:203], v[16:19]
	v_mfma_f32_16x16x32_bf16 v[4:7], v[216:219], v[208:211], v[4:7]
	v_mfma_f32_16x16x32_bf16 v[0:3], v[224:227], v[208:211], v[0:3]
	v_mfma_f32_16x16x32_bf16 v[52:55], v[220:223], v[188:191], v[52:55]
	v_mfma_f32_16x16x32_bf16 v[48:51], v[228:231], v[188:191], v[48:51]
	v_mfma_f32_16x16x32_bf16 v[36:39], v[220:223], v[196:199], v[36:39]
	v_mfma_f32_16x16x32_bf16 v[32:35], v[228:231], v[196:199], v[32:35]
	v_mfma_f32_16x16x32_bf16 v[20:23], v[220:223], v[204:207], v[20:23]
	v_mfma_f32_16x16x32_bf16 v[16:19], v[228:231], v[204:207], v[16:19]
	v_mfma_f32_16x16x32_bf16 v[4:7], v[220:223], v[212:215], v[4:7]
	v_mfma_f32_16x16x32_bf16 v[0:3], v[228:231], v[212:215], v[0:3]
	s_add_i32 s25, s25, 2
	s_add_u32 s30, s30, 0x100
	s_addc_u32 s31, s31, 0
	s_add_u32 s17, s17, 0x100
	s_addc_u32 s24, s24, 0
	s_cmp_gt_u32 s25, 13
	s_cbranch_scc1 .Lgin_exit
	s_barrier
	s_branch .LBB0_271

.Lgin_epi:
	s_nop 0
	s_nop 0
	s_nop 0
	s_nop 0
	s_nop 0
	s_nop 0
	s_nop 0
	s_nop 0
	s_waitcnt vmcnt(0)
	v_fmamk_f32 v130, v156, 0x3a800000, v235
	v_mul_f32_e32 v131, 0x4b800000, v130
	v_cmp_gt_f32_e32 vcc, s86, v130
	s_cmp_lt_i32 s40, 4
	s_cselect_b64 s[14:15], -1, 0
	v_cndmask_b32_e32 v130, v130, v131, vcc
	v_rsq_f32_e32 v130, v130
	s_cmp_gt_i32 s40, 3
	v_mul_f32_e32 v131, 0x45800000, v130
	v_cndmask_b32_e32 v156, v130, v131, vcc
	v_pk_mul_f32 v[126:127], v[156:157], v[126:127] op_sel_hi:[0,1]
	v_pk_mul_f32 v[124:125], v[156:157], v[124:125] op_sel_hi:[0,1]
	v_pk_mul_f32 v[158:159], v[156:157], v[122:123] op_sel_hi:[0,1]
	v_pk_mul_f32 v[160:161], v[156:157], v[120:121] op_sel_hi:[0,1]
	s_cbranch_scc1 .LBB0_274
	v_mul_f32_e32 v121, 0x3d372713, v160
	v_mul_f32_e32 v121, v160, v121
	v_fma_f32 v121, v160, v121, v160
	v_mul_f32_e32 v121, 0x3fcc422a, v121
	v_mul_f32_e32 v121, 0xbfb8aa3b, v121
	v_exp_f32_e32 v121, v121
	v_mul_f32_e32 v120, 0x3d372713, v124
	v_mul_f32_e32 v120, v124, v120
	v_mov_b32_e32 v123, v125
	v_add_f32_e32 v121, 1.0, v121
	v_rcp_f32_e32 v122, v121
	v_mul_f32_e32 v121, 0x3d372713, v125
	v_mul_f32_e32 v121, v125, v121
	v_fma_f32 v120, v124, v120, v124
	v_fmac_f32_e32 v123, v123, v121
	v_mul_f32_e32 v120, 0x3fcc422a, v120
	v_mul_f32_e32 v121, 0x3fcc422a, v123
	v_mul_f32_e32 v120, 0xbfb8aa3b, v120
	v_mul_f32_e32 v121, 0xbfb8aa3b, v121
	v_mul_f32_e32 v131, 0x3d372713, v158
	v_exp_f32_e32 v120, v120
	v_exp_f32_e32 v121, v121
	v_mul_f32_e32 v131, v158, v131
	v_fma_f32 v131, v158, v131, v158
	v_mul_f32_e32 v131, 0x3fcc422a, v131
	v_mul_f32_e32 v131, 0xbfb8aa3b, v131
	v_add_f32_e32 v120, 1.0, v120
	v_add_f32_e32 v121, 1.0, v121
	v_exp_f32_e32 v131, v131
	v_rcp_f32_e32 v120, v120
	v_rcp_f32_e32 v121, v121
	v_mul_f32_e32 v123, 0x3d372713, v161
	v_mul_f32_e32 v123, v161, v123
	v_mov_b32_e32 v130, v161
	v_fmac_f32_e32 v130, v130, v123
	v_add_f32_e32 v131, 1.0, v131
	v_mul_f32_e32 v123, 0x3fcc422a, v130
	v_mul_f32_e32 v130, 0x3d372713, v126
	v_rcp_f32_e32 v132, v131
	v_mul_f32_e32 v131, 0x3d372713, v127
	v_pk_mul_f32 v[124:125], v[124:125], v[120:121]
	v_mul_f32_e32 v120, 0x3d372713, v159
	v_mul_f32_e32 v130, v126, v130
	v_mul_f32_e32 v131, v127, v131
	v_mul_f32_e32 v120, v159, v120
	v_fma_f32 v130, v126, v130, v126
	v_fma_f32 v131, v127, v131, v127
	v_fma_f32 v120, v159, v120, v159
	v_mul_f32_e32 v130, 0x3fcc422a, v130
	v_mul_f32_e32 v131, 0x3fcc422a, v131
	v_mul_f32_e32 v120, 0x3fcc422a, v120
	v_mul_f32_e32 v123, 0xbfb8aa3b, v123
	v_mul_f32_e32 v130, 0xbfb8aa3b, v130
	v_mul_f32_e32 v131, 0xbfb8aa3b, v131
	v_mul_f32_e32 v120, 0xbfb8aa3b, v120
	v_exp_f32_e32 v123, v123
	v_exp_f32_e32 v130, v130
	v_exp_f32_e32 v131, v131
	v_exp_f32_e32 v120, v120
	v_add_f32_e32 v123, 1.0, v123
	v_add_f32_e32 v130, 1.0, v130
	v_add_f32_e32 v131, 1.0, v131
	v_add_f32_e32 v120, 1.0, v120
	v_rcp_f32_e32 v123, v123
	v_rcp_f32_e32 v130, v130
	v_rcp_f32_e32 v131, v131
	v_rcp_f32_e32 v133, v120
	v_pk_mul_f32 v[160:161], v[160:161], v[122:123]
	v_pk_mul_f32 v[126:127], v[126:127], v[130:131]
	v_pk_mul_f32 v[158:159], v[158:159], v[132:133]

.LBB0_344:
	s_add_u32 s30, s18, 0xb0080
	s_addc_u32 s31, s19, 0
	s_add_u32 s0, s14, 0x100
	v_mov_b32_e32 v0, 0
	s_addc_u32 s1, s15, 0
	s_mov_b32 s25, -2
	v_mov_b32_e32 v1, v0
	v_mov_b32_e32 v2, v0
	v_mov_b32_e32 v3, v0
	v_mov_b32_e32 v4, v0
	v_mov_b32_e32 v5, v0
	v_mov_b32_e32 v6, v0
	v_mov_b32_e32 v7, v0
	v_mov_b32_e32 v16, v0
	v_mov_b32_e32 v17, v0
	v_mov_b32_e32 v18, v0
	v_mov_b32_e32 v19, v0
	v_mov_b32_e32 v20, v0
	v_mov_b32_e32 v21, v0
	v_mov_b32_e32 v22, v0
	v_mov_b32_e32 v23, v0
	v_mov_b32_e32 v32, v0
	v_mov_b32_e32 v33, v0
	v_mov_b32_e32 v34, v0
	v_mov_b32_e32 v35, v0
	v_mov_b32_e32 v36, v0
	v_mov_b32_e32 v37, v0
	v_mov_b32_e32 v38, v0
	v_mov_b32_e32 v39, v0
	v_mov_b32_e32 v48, v0
	v_mov_b32_e32 v49, v0
	v_mov_b32_e32 v50, v0
	v_mov_b32_e32 v51, v0
	v_mov_b32_e32 v52, v0
	v_mov_b32_e32 v53, v0
	v_mov_b32_e32 v54, v0
	v_mov_b32_e32 v55, v0
	v_mov_b32_e32 v8, v0
	v_mov_b32_e32 v9, v0
	v_mov_b32_e32 v10, v0
	v_mov_b32_e32 v11, v0
	v_mov_b32_e32 v12, v0
	v_mov_b32_e32 v13, v0
	v_mov_b32_e32 v14, v0
	v_mov_b32_e32 v15, v0
	v_mov_b32_e32 v24, v0
	v_mov_b32_e32 v25, v0
	v_mov_b32_e32 v26, v0
	v_mov_b32_e32 v27, v0
	v_mov_b32_e32 v28, v0
	v_mov_b32_e32 v29, v0
	v_mov_b32_e32 v30, v0
	v_mov_b32_e32 v31, v0
	v_mov_b32_e32 v40, v0
	v_mov_b32_e32 v41, v0
	v_mov_b32_e32 v42, v0
	v_mov_b32_e32 v43, v0
	v_mov_b32_e32 v44, v0
	v_mov_b32_e32 v45, v0
	v_mov_b32_e32 v46, v0
	v_mov_b32_e32 v47, v0
	v_mov_b32_e32 v56, v0
	v_mov_b32_e32 v57, v0
	v_mov_b32_e32 v58, v0
	v_mov_b32_e32 v59, v0
	v_mov_b32_e32 v60, v0
	v_mov_b32_e32 v61, v0
	v_mov_b32_e32 v62, v0
	v_mov_b32_e32 v63, v0
	v_mov_b32_e32 v64, v0
	v_mov_b32_e32 v65, v0
	v_mov_b32_e32 v66, v0
	v_mov_b32_e32 v67, v0
	v_mov_b32_e32 v68, v0
	v_mov_b32_e32 v69, v0
	v_mov_b32_e32 v70, v0
	v_mov_b32_e32 v71, v0
	v_mov_b32_e32 v80, v0
	v_mov_b32_e32 v81, v0
	v_mov_b32_e32 v82, v0
	v_mov_b32_e32 v83, v0
	v_mov_b32_e32 v84, v0
	v_mov_b32_e32 v85, v0
	v_mov_b32_e32 v86, v0
	v_mov_b32_e32 v87, v0
	v_mov_b32_e32 v96, v0
	v_mov_b32_e32 v97, v0
	v_mov_b32_e32 v98, v0
	v_mov_b32_e32 v99, v0
	v_mov_b32_e32 v100, v0
	v_mov_b32_e32 v101, v0
	v_mov_b32_e32 v102, v0
	v_mov_b32_e32 v103, v0
	v_mov_b32_e32 v112, v0
	v_mov_b32_e32 v113, v0
	v_mov_b32_e32 v114, v0
	v_mov_b32_e32 v115, v0
	v_mov_b32_e32 v116, v0
	v_mov_b32_e32 v117, v0
	v_mov_b32_e32 v118, v0
	v_mov_b32_e32 v119, v0
	v_mov_b32_e32 v72, v0
	v_mov_b32_e32 v73, v0
	v_mov_b32_e32 v74, v0
	v_mov_b32_e32 v75, v0
	v_mov_b32_e32 v76, v0
	v_mov_b32_e32 v77, v0
	v_mov_b32_e32 v78, v0
	v_mov_b32_e32 v79, v0
	v_mov_b32_e32 v88, v0
	v_mov_b32_e32 v89, v0
	v_mov_b32_e32 v90, v0
	v_mov_b32_e32 v91, v0
	v_mov_b32_e32 v92, v0
	v_mov_b32_e32 v93, v0
	v_mov_b32_e32 v94, v0
	v_mov_b32_e32 v95, v0
	v_mov_b32_e32 v104, v0
	v_mov_b32_e32 v105, v0
	v_mov_b32_e32 v106, v0
	v_mov_b32_e32 v107, v0
	v_mov_b32_e32 v108, v0
	v_mov_b32_e32 v109, v0
	v_mov_b32_e32 v110, v0
	v_mov_b32_e32 v111, v0
	v_mov_b32_e32 v120, v0
	v_mov_b32_e32 v121, v0
	v_mov_b32_e32 v122, v0
	v_mov_b32_e32 v123, v0
	v_mov_b32_e32 v124, v0
	v_mov_b32_e32 v125, v0
	v_mov_b32_e32 v126, v0
	v_mov_b32_e32 v127, v0
	s_cmpk_gt_u32 s48, 0xff
	s_cbranch_scc0 .Lg2_enter
	s_barrier
.Lg2_enter:
.LBB0_345:
	s_add_u32 s14, s30, 0xfff50080
	s_addc_u32 s15, s31, -1
	s_add_i32 s20, 16, 0x10000
	v_add_u32_e32 v130, s20, v160
	ds_read_b128 v[154:157], v130
	ds_read_b128 v[164:167], v130 offset:1024
	ds_read_b128 v[168:171], v130 offset:2048
	ds_read_b128 v[172:175], v130 offset:3072
	s_cmp_eq_u32 s25, 40
	s_cselect_b32 s19, s9, s15
	s_cselect_b32 s18, s8, s14
	s_cselect_b32 s15, s13, s1
	s_cselect_b32 s14, s12, s0
	v_lshl_add_u64 v[130:131], s[30:31], 0, v[150:151]
	s_add_i32 m0, s34, 0xc000
	ds_read_b128 v[176:179], v162
	ds_read_b128 v[180:183], v162 offset:1024
	ds_read_b128 v[184:187], v162 offset:2048
	ds_read_b128 v[188:191], v162 offset:3072
	ds_read_b128 v[192:195], v162 offset:4096
	ds_read_b128 v[196:199], v162 offset:5120
	ds_read_b128 v[200:203], v162 offset:6144
	ds_read_b128 v[204:207], v162 offset:7168
	global_load_lds_dwordx4 v[130:131], off
	v_lshl_add_u64 v[130:131], s[30:31], 0, v[152:153]
	s_add_i32 m0, s34, 0xe000
	s_nop 0
	global_load_lds_dwordx4 v[130:131], off
	s_add_i32 s42, 16, 0x14000
	v_add_u32_e32 v130, s42, v160
	ds_read_b128 v[208:211], v130
	ds_read_b128 v[212:215], v130 offset:1024
	ds_read_b128 v[216:219], v130 offset:2048
	ds_read_b128 v[220:223], v130 offset:3072
	s_waitcnt vmcnt(8) lgkmcnt(0)
	s_barrier
	v_mfma_f32_16x16x32_bf16 v[124:127], v[154:157], v[176:179], v[124:127]
	v_mfma_f32_16x16x32_bf16 v[120:123], v[168:171], v[176:179], v[120:123]
	v_mfma_f32_16x16x32_bf16 v[108:111], v[154:157], v[184:187], v[108:111]
	v_mfma_f32_16x16x32_bf16 v[104:107], v[168:171], v[184:187], v[104:107]
	v_mfma_f32_16x16x32_bf16 v[92:95], v[154:157], v[192:195], v[92:95]
	v_mfma_f32_16x16x32_bf16 v[88:91], v[168:171], v[192:195], v[88:91]
	v_mfma_f32_16x16x32_bf16 v[76:79], v[154:157], v[200:203], v[76:79]
	v_mfma_f32_16x16x32_bf16 v[72:75], v[168:171], v[200:203], v[72:75]
	v_mfma_f32_16x16x32_bf16 v[124:127], v[164:167], v[180:183], v[124:127]
	v_mfma_f32_16x16x32_bf16 v[120:123], v[172:175], v[180:183], v[120:123]
	v_mfma_f32_16x16x32_bf16 v[108:111], v[164:167], v[188:191], v[108:111]
	v_mfma_f32_16x16x32_bf16 v[104:107], v[172:175], v[188:191], v[104:107]
	v_mfma_f32_16x16x32_bf16 v[92:95], v[164:167], v[196:199], v[92:95]
	v_mfma_f32_16x16x32_bf16 v[88:91], v[172:175], v[196:199], v[88:91]
	v_mfma_f32_16x16x32_bf16 v[76:79], v[164:167], v[204:207], v[76:79]
	v_mfma_f32_16x16x32_bf16 v[72:75], v[172:175], v[204:207], v[72:75]
	v_mfma_f32_16x16x32_bf16 v[116:119], v[208:211], v[176:179], v[116:119]
	v_mfma_f32_16x16x32_bf16 v[112:115], v[216:219], v[176:179], v[112:115]
	v_mfma_f32_16x16x32_bf16 v[100:103], v[208:211], v[184:187], v[100:103]
	v_mfma_f32_16x16x32_bf16 v[96:99], v[216:219], v[184:187], v[96:99]
	v_mfma_f32_16x16x32_bf16 v[84:87], v[208:211], v[192:195], v[84:87]
	v_mfma_f32_16x16x32_bf16 v[80:83], v[216:219], v[192:195], v[80:83]
	v_mfma_f32_16x16x32_bf16 v[68:71], v[208:211], v[200:203], v[68:71]
	v_mfma_f32_16x16x32_bf16 v[64:67], v[216:219], v[200:203], v[64:67]
	v_mfma_f32_16x16x32_bf16 v[116:119], v[212:215], v[180:183], v[116:119]
	v_mfma_f32_16x16x32_bf16 v[112:115], v[220:223], v[180:183], v[112:115]
	v_mfma_f32_16x16x32_bf16 v[100:103], v[212:215], v[188:191], v[100:103]
	v_mfma_f32_16x16x32_bf16 v[96:99], v[220:223], v[188:191], v[96:99]
	v_mfma_f32_16x16x32_bf16 v[84:87], v[212:215], v[196:199], v[84:87]
	v_mfma_f32_16x16x32_bf16 v[80:83], v[220:223], v[196:199], v[80:83]
	v_mfma_f32_16x16x32_bf16 v[68:71], v[212:215], v[204:207], v[68:71]
	v_mfma_f32_16x16x32_bf16 v[64:67], v[220:223], v[204:207], v[64:67]
	s_barrier
	ds_read_b128 v[176:179], v162 offset:16384
	ds_read_b128 v[180:183], v162 offset:17408
	ds_read_b128 v[184:187], v162 offset:18432
	ds_read_b128 v[188:191], v162 offset:19456
	ds_read_b128 v[192:195], v162 offset:20480
	ds_read_b128 v[196:199], v162 offset:21504
	ds_read_b128 v[200:203], v162 offset:22528
	ds_read_b128 v[204:207], v162 offset:23552
	s_add_i32 s20, s20, s5
	v_lshl_add_u64 v[130:131], s[14:15], 0, v[128:129]
	s_mov_b32 m0, s20
	v_lshl_add_u64 v[132:133], s[14:15], 0, v[148:149]
	global_load_lds_dwordx4 v[130:131], off
	s_add_i32 m0, s20, 0x2000
	s_nop 0
	global_load_lds_dwordx4 v[132:133], off
	s_mov_b32 m0, s34
	v_lshl_add_u64 v[134:135], s[18:19], 0, v[144:145]
	global_load_lds_dwordx4 v[134:135], off
	v_lshl_add_u64 v[136:137], s[18:19], 0, v[146:147]
	s_mov_b32 m0, s35
	s_nop 0
	global_load_lds_dwordx4 v[136:137], off
	s_add_u32 s40, s14, 0xb0000
	s_addc_u32 s41, s15, 0
	s_add_i32 s20, s42, s5
	v_lshl_add_u64 v[138:139], s[40:41], 0, v[128:129]
	s_mov_b32 m0, s20
	s_nop 0
	global_load_lds_dwordx4 v[138:139], off
	v_lshl_add_u64 v[138:139], s[40:41], 0, v[148:149]
	s_add_i32 m0, s20, 0x2000
	s_nop 0
	global_load_lds_dwordx4 v[138:139], off
	s_waitcnt vmcnt(8) lgkmcnt(0)
	s_barrier
	v_mfma_f32_16x16x32_bf16 v[60:63], v[154:157], v[176:179], v[60:63]
	v_mfma_f32_16x16x32_bf16 v[56:59], v[168:171], v[176:179], v[56:59]
	v_mfma_f32_16x16x32_bf16 v[44:47], v[154:157], v[184:187], v[44:47]
	v_mfma_f32_16x16x32_bf16 v[40:43], v[168:171], v[184:187], v[40:43]
	v_mfma_f32_16x16x32_bf16 v[28:31], v[154:157], v[192:195], v[28:31]
	v_mfma_f32_16x16x32_bf16 v[24:27], v[168:171], v[192:195], v[24:27]
	v_mfma_f32_16x16x32_bf16 v[12:15], v[154:157], v[200:203], v[12:15]
	v_mfma_f32_16x16x32_bf16 v[8:11], v[168:171], v[200:203], v[8:11]
	v_mfma_f32_16x16x32_bf16 v[60:63], v[164:167], v[180:183], v[60:63]
	v_mfma_f32_16x16x32_bf16 v[56:59], v[172:175], v[180:183], v[56:59]
	v_mfma_f32_16x16x32_bf16 v[44:47], v[164:167], v[188:191], v[44:47]
	v_mfma_f32_16x16x32_bf16 v[40:43], v[172:175], v[188:191], v[40:43]
	v_mfma_f32_16x16x32_bf16 v[28:31], v[164:167], v[196:199], v[28:31]
	v_mfma_f32_16x16x32_bf16 v[24:27], v[172:175], v[196:199], v[24:27]
	v_mfma_f32_16x16x32_bf16 v[12:15], v[164:167], v[204:207], v[12:15]
	v_mfma_f32_16x16x32_bf16 v[8:11], v[172:175], v[204:207], v[8:11]
	v_mfma_f32_16x16x32_bf16 v[52:55], v[208:211], v[176:179], v[52:55]
	v_mfma_f32_16x16x32_bf16 v[48:51], v[216:219], v[176:179], v[48:51]
	v_mfma_f32_16x16x32_bf16 v[36:39], v[208:211], v[184:187], v[36:39]
	v_mfma_f32_16x16x32_bf16 v[32:35], v[216:219], v[184:187], v[32:35]
	v_mfma_f32_16x16x32_bf16 v[20:23], v[208:211], v[192:195], v[20:23]
	v_mfma_f32_16x16x32_bf16 v[16:19], v[216:219], v[192:195], v[16:19]
	v_mfma_f32_16x16x32_bf16 v[4:7], v[208:211], v[200:203], v[4:7]
	v_mfma_f32_16x16x32_bf16 v[0:3], v[216:219], v[200:203], v[0:3]
	v_mfma_f32_16x16x32_bf16 v[52:55], v[212:215], v[180:183], v[52:55]
	v_mfma_f32_16x16x32_bf16 v[48:51], v[220:223], v[180:183], v[48:51]
	v_mfma_f32_16x16x32_bf16 v[36:39], v[212:215], v[188:191], v[36:39]
	v_mfma_f32_16x16x32_bf16 v[32:35], v[220:223], v[188:191], v[32:35]
	v_mfma_f32_16x16x32_bf16 v[20:23], v[212:215], v[196:199], v[20:23]
	v_mfma_f32_16x16x32_bf16 v[16:19], v[220:223], v[196:199], v[16:19]
	v_mfma_f32_16x16x32_bf16 v[4:7], v[212:215], v[204:207], v[4:7]
	v_mfma_f32_16x16x32_bf16 v[0:3], v[220:223], v[204:207], v[0:3]
	s_add_i32 s20, 16, 0x18000
	v_add_u32_e32 v138, s20, v160
	s_barrier
	ds_read_b128 v[154:157], v138
	ds_read_b128 v[164:167], v138 offset:1024
	ds_read_b128 v[168:171], v138 offset:2048
	ds_read_b128 v[172:175], v138 offset:3072
	s_add_u32 s18, s18, 0xb0000
	s_addc_u32 s19, s19, 0
	s_mov_b32 m0, s36
	v_lshl_add_u64 v[158:159], s[18:19], 0, v[144:145]
	ds_read_b128 v[176:179], v162 offset:32768
	ds_read_b128 v[180:183], v162 offset:33792
	ds_read_b128 v[184:187], v162 offset:34816
	ds_read_b128 v[188:191], v162 offset:35840
	ds_read_b128 v[192:195], v162 offset:36864
	ds_read_b128 v[196:199], v162 offset:37888
	ds_read_b128 v[200:203], v162 offset:38912
	ds_read_b128 v[204:207], v162 offset:39936
	global_load_lds_dwordx4 v[158:159], off
	v_lshl_add_u64 v[158:159], s[18:19], 0, v[146:147]
	s_mov_b32 m0, s37
	s_nop 0
	global_load_lds_dwordx4 v[158:159], off
	s_add_i32 s18, 16, 0x1c000
	v_add_u32_e32 v138, s18, v160
	ds_read_b128 v[208:211], v138
	ds_read_b128 v[212:215], v138 offset:1024
	ds_read_b128 v[216:219], v138 offset:2048
	ds_read_b128 v[220:223], v138 offset:3072
	s_waitcnt vmcnt(8) lgkmcnt(0)
	s_barrier
	v_mfma_f32_16x16x32_bf16 v[124:127], v[154:157], v[176:179], v[124:127]
	v_mfma_f32_16x16x32_bf16 v[120:123], v[168:171], v[176:179], v[120:123]
	v_mfma_f32_16x16x32_bf16 v[108:111], v[154:157], v[184:187], v[108:111]
	v_mfma_f32_16x16x32_bf16 v[104:107], v[168:171], v[184:187], v[104:107]
	v_mfma_f32_16x16x32_bf16 v[92:95], v[154:157], v[192:195], v[92:95]
	v_mfma_f32_16x16x32_bf16 v[88:91], v[168:171], v[192:195], v[88:91]
	v_mfma_f32_16x16x32_bf16 v[76:79], v[154:157], v[200:203], v[76:79]
	v_mfma_f32_16x16x32_bf16 v[72:75], v[168:171], v[200:203], v[72:75]
	v_mfma_f32_16x16x32_bf16 v[124:127], v[164:167], v[180:183], v[124:127]
	v_mfma_f32_16x16x32_bf16 v[120:123], v[172:175], v[180:183], v[120:123]
	v_mfma_f32_16x16x32_bf16 v[108:111], v[164:167], v[188:191], v[108:111]
	v_mfma_f32_16x16x32_bf16 v[104:107], v[172:175], v[188:191], v[104:107]
	v_mfma_f32_16x16x32_bf16 v[92:95], v[164:167], v[196:199], v[92:95]
	v_mfma_f32_16x16x32_bf16 v[88:91], v[172:175], v[196:199], v[88:91]
	v_mfma_f32_16x16x32_bf16 v[76:79], v[164:167], v[204:207], v[76:79]
	v_mfma_f32_16x16x32_bf16 v[72:75], v[172:175], v[204:207], v[72:75]
	v_mfma_f32_16x16x32_bf16 v[116:119], v[208:211], v[176:179], v[116:119]
	v_mfma_f32_16x16x32_bf16 v[112:115], v[216:219], v[176:179], v[112:115]
	v_mfma_f32_16x16x32_bf16 v[100:103], v[208:211], v[184:187], v[100:103]
	v_mfma_f32_16x16x32_bf16 v[96:99], v[216:219], v[184:187], v[96:99]
	v_mfma_f32_16x16x32_bf16 v[84:87], v[208:211], v[192:195], v[84:87]
	v_mfma_f32_16x16x32_bf16 v[80:83], v[216:219], v[192:195], v[80:83]
	v_mfma_f32_16x16x32_bf16 v[68:71], v[208:211], v[200:203], v[68:71]
	v_mfma_f32_16x16x32_bf16 v[64:67], v[216:219], v[200:203], v[64:67]
	v_mfma_f32_16x16x32_bf16 v[116:119], v[212:215], v[180:183], v[116:119]
	v_mfma_f32_16x16x32_bf16 v[112:115], v[220:223], v[180:183], v[112:115]
	v_mfma_f32_16x16x32_bf16 v[100:103], v[212:215], v[188:191], v[100:103]
	v_mfma_f32_16x16x32_bf16 v[96:99], v[220:223], v[188:191], v[96:99]
	v_mfma_f32_16x16x32_bf16 v[84:87], v[212:215], v[196:199], v[84:87]
	v_mfma_f32_16x16x32_bf16 v[80:83], v[220:223], v[196:199], v[80:83]
	v_mfma_f32_16x16x32_bf16 v[68:71], v[212:215], v[204:207], v[68:71]
	v_mfma_f32_16x16x32_bf16 v[64:67], v[220:223], v[204:207], v[64:67]
	s_barrier
	ds_read_b128 v[176:179], v162 offset:49152
	ds_read_b128 v[180:183], v162 offset:50176
	ds_read_b128 v[184:187], v162 offset:51200
	ds_read_b128 v[188:191], v162 offset:52224
	ds_read_b128 v[192:195], v162 offset:53248
	ds_read_b128 v[196:199], v162 offset:54272
	ds_read_b128 v[200:203], v162 offset:55296
	ds_read_b128 v[204:207], v162 offset:56320
	s_add_i32 s19, s20, s5
	v_lshl_add_u64 v[130:131], v[130:131], 0, s[28:29]
	s_mov_b32 m0, s19
	s_nop 0
	global_load_lds_dwordx4 v[130:131], off
	v_lshl_add_u64 v[130:131], v[132:133], 0, s[28:29]
	s_add_i32 m0, s19, 0x2000
	s_nop 0
	global_load_lds_dwordx4 v[130:131], off
	s_mov_b32 m0, s44
	v_lshl_add_u64 v[130:131], v[134:135], 0, s[28:29]
	global_load_lds_dwordx4 v[130:131], off
	v_lshl_add_u64 v[130:131], v[136:137], 0, s[28:29]
	s_mov_b32 m0, s45
	s_nop 0
	global_load_lds_dwordx4 v[130:131], off
	s_add_u32 s14, s14, 0xb0080
	s_addc_u32 s15, s15, 0
	s_add_i32 s18, s18, s5
	v_lshl_add_u64 v[130:131], s[14:15], 0, v[128:129]
	s_mov_b32 m0, s18
	s_nop 0
	global_load_lds_dwordx4 v[130:131], off
	v_lshl_add_u64 v[130:131], s[14:15], 0, v[148:149]
	s_add_i32 m0, s18, 0x2000
	s_nop 0
	global_load_lds_dwordx4 v[130:131], off
	s_waitcnt vmcnt(8) lgkmcnt(0)
	s_barrier
	v_mfma_f32_16x16x32_bf16 v[60:63], v[154:157], v[176:179], v[60:63]
	v_mfma_f32_16x16x32_bf16 v[56:59], v[168:171], v[176:179], v[56:59]
	v_mfma_f32_16x16x32_bf16 v[44:47], v[154:157], v[184:187], v[44:47]
	v_mfma_f32_16x16x32_bf16 v[40:43], v[168:171], v[184:187], v[40:43]
	v_mfma_f32_16x16x32_bf16 v[28:31], v[154:157], v[192:195], v[28:31]
	v_mfma_f32_16x16x32_bf16 v[24:27], v[168:171], v[192:195], v[24:27]
	v_mfma_f32_16x16x32_bf16 v[12:15], v[154:157], v[200:203], v[12:15]
	v_mfma_f32_16x16x32_bf16 v[8:11], v[168:171], v[200:203], v[8:11]
	v_mfma_f32_16x16x32_bf16 v[60:63], v[164:167], v[180:183], v[60:63]
	v_mfma_f32_16x16x32_bf16 v[56:59], v[172:175], v[180:183], v[56:59]
	v_mfma_f32_16x16x32_bf16 v[44:47], v[164:167], v[188:191], v[44:47]
	v_mfma_f32_16x16x32_bf16 v[40:43], v[172:175], v[188:191], v[40:43]
	v_mfma_f32_16x16x32_bf16 v[28:31], v[164:167], v[196:199], v[28:31]
	v_mfma_f32_16x16x32_bf16 v[24:27], v[172:175], v[196:199], v[24:27]
	v_mfma_f32_16x16x32_bf16 v[12:15], v[164:167], v[204:207], v[12:15]
	v_mfma_f32_16x16x32_bf16 v[8:11], v[172:175], v[204:207], v[8:11]
	v_mfma_f32_16x16x32_bf16 v[52:55], v[208:211], v[176:179], v[52:55]
	v_mfma_f32_16x16x32_bf16 v[48:51], v[216:219], v[176:179], v[48:51]
	v_mfma_f32_16x16x32_bf16 v[36:39], v[208:211], v[184:187], v[36:39]
	v_mfma_f32_16x16x32_bf16 v[32:35], v[216:219], v[184:187], v[32:35]
	v_mfma_f32_16x16x32_bf16 v[20:23], v[208:211], v[192:195], v[20:23]
	v_mfma_f32_16x16x32_bf16 v[16:19], v[216:219], v[192:195], v[16:19]
	v_mfma_f32_16x16x32_bf16 v[4:7], v[208:211], v[200:203], v[4:7]
	v_mfma_f32_16x16x32_bf16 v[0:3], v[216:219], v[200:203], v[0:3]
	v_mfma_f32_16x16x32_bf16 v[52:55], v[212:215], v[180:183], v[52:55]
	v_mfma_f32_16x16x32_bf16 v[48:51], v[220:223], v[180:183], v[48:51]
	v_mfma_f32_16x16x32_bf16 v[36:39], v[212:215], v[188:191], v[36:39]
	v_mfma_f32_16x16x32_bf16 v[32:35], v[220:223], v[188:191], v[32:35]
	v_mfma_f32_16x16x32_bf16 v[20:23], v[212:215], v[196:199], v[20:23]
	v_mfma_f32_16x16x32_bf16 v[16:19], v[220:223], v[196:199], v[16:19]
	v_mfma_f32_16x16x32_bf16 v[4:7], v[212:215], v[204:207], v[4:7]
	v_mfma_f32_16x16x32_bf16 v[0:3], v[220:223], v[204:207], v[0:3]
	s_add_i32 s25, s25, 2
	s_add_u32 s30, s30, 0x100
	s_addc_u32 s31, s31, 0
	s_add_u32 s0, s0, 0x100
	s_addc_u32 s1, s1, 0
	s_cmp_gt_u32 s25, 41
	s_cbranch_scc1 .Lg2_exit
	s_barrier
	s_branch .LBB0_345

.Lg2_epi:
	s_nop 0
	s_nop 0
	s_nop 0
	s_nop 0
	s_nop 0
	s_nop 0
	s_nop 0
	s_nop 0
	s_cmp_lt_i32 s47, 0
	s_cselect_b64 s[14:15], -1, 0
	s_cmp_gt_i32 s47, -1
	s_cbranch_scc1 .LBB0_348
	v_mul_f32_e32 v131, 0x3d372713, v120
	v_mul_f32_e32 v131, v120, v131
	v_fma_f32 v131, v120, v131, v120
	v_mul_f32_e32 v131, 0x3fcc422a, v131
	v_mul_f32_e32 v131, 0xbfb8aa3b, v131
	v_exp_f32_e32 v131, v131
	v_mul_f32_e32 v130, 0x3d372713, v124
	v_mul_f32_e32 v130, v124, v130
	v_fma_f32 v130, v124, v130, v124
	v_add_f32_e32 v131, 1.0, v131
	v_rcp_f32_e32 v132, v131
	v_mul_f32_e32 v131, 0x3d372713, v125
	v_mul_f32_e32 v131, v125, v131
	v_fma_f32 v131, v125, v131, v125
	v_mul_f32_e32 v130, 0x3fcc422a, v130
	v_mul_f32_e32 v131, 0x3fcc422a, v131
	v_mul_f32_e32 v130, 0xbfb8aa3b, v130
	v_mul_f32_e32 v131, 0xbfb8aa3b, v131
	v_mul_f32_e32 v135, 0x3d372713, v122
	v_exp_f32_e32 v130, v130
	v_exp_f32_e32 v131, v131
	v_mul_f32_e32 v135, v122, v135
	v_fma_f32 v135, v122, v135, v122
	v_mul_f32_e32 v135, 0x3fcc422a, v135
	v_mul_f32_e32 v135, 0xbfb8aa3b, v135
	v_add_f32_e32 v130, 1.0, v130
	v_add_f32_e32 v131, 1.0, v131
	v_exp_f32_e32 v135, v135
	v_rcp_f32_e32 v130, v130
	v_rcp_f32_e32 v131, v131
	v_mul_f32_e32 v133, 0x3d372713, v121
	v_add_f32_e32 v135, 1.0, v135
	v_mul_f32_e32 v134, 0x3d372713, v126
	v_rcp_f32_e32 v136, v135
	v_mul_f32_e32 v135, 0x3d372713, v127
	v_pk_mul_f32 v[124:125], v[124:125], v[130:131]
	v_mul_f32_e32 v130, 0x3d372713, v123
	v_mul_f32_e32 v133, v121, v133
	v_mul_f32_e32 v134, v126, v134
	v_mul_f32_e32 v135, v127, v135
	v_mul_f32_e32 v130, v123, v130
	v_fma_f32 v133, v121, v133, v121
	v_fma_f32 v134, v126, v134, v126
	v_fma_f32 v135, v127, v135, v127
	v_fma_f32 v130, v123, v130, v123
	v_mul_f32_e32 v133, 0x3fcc422a, v133
	v_mul_f32_e32 v134, 0x3fcc422a, v134
	v_mul_f32_e32 v135, 0x3fcc422a, v135
	v_mul_f32_e32 v130, 0x3fcc422a, v130
	v_mul_f32_e32 v133, 0xbfb8aa3b, v133
	v_mul_f32_e32 v134, 0xbfb8aa3b, v134
	v_mul_f32_e32 v135, 0xbfb8aa3b, v135
	v_mul_f32_e32 v130, 0xbfb8aa3b, v130
	v_exp_f32_e32 v133, v133
	v_exp_f32_e32 v134, v134
	v_exp_f32_e32 v135, v135
	v_exp_f32_e32 v130, v130
	v_add_f32_e32 v133, 1.0, v133
	v_add_f32_e32 v134, 1.0, v134
	v_add_f32_e32 v135, 1.0, v135
	v_add_f32_e32 v130, 1.0, v130
	v_rcp_f32_e32 v133, v133
	v_rcp_f32_e32 v134, v134
	v_rcp_f32_e32 v135, v135
	v_rcp_f32_e32 v137, v130
	v_pk_mul_f32 v[120:121], v[120:121], v[132:133]
	v_pk_mul_f32 v[126:127], v[126:127], v[134:135]
	v_pk_mul_f32 v[122:123], v[122:123], v[136:137]

.LBB0_390:
	v_mov_b64_e32 v[0:1], 0x1080
	s_ashr_i32 s13, s12, 31
	v_cmp_lt_i64_e32 vcc, s[30:31], v[0:1]
	s_lshl_b64 s[24:25], s[12:13], 19
	v_readlane_b32 s30, v252, 55
	v_readlane_b32 s31, v252, 56
	s_add_u32 s40, s30, s24
	s_addc_u32 s41, s31, s25
	v_lshl_add_u32 v154, s20, 8, v143
	v_readlane_b32 s30, v252, 43
	v_ashrrev_i32_e32 v155, 31, v154
	v_readlane_b32 s31, v252, 44
	s_and_b64 s[24:25], vcc, exec
	s_cselect_b32 s1, s41, s19
	v_lshl_add_u64 v[0:1], v[154:155], 2, s[30:31]
	global_load_dword v165, v[0:1], off
	global_load_dword v164, v[0:1], off offset:64
	global_load_dword v163, v[0:1], off offset:128
	global_load_dword v162, v[0:1], off offset:192
	global_load_dword v161, v[0:1], off offset:512
	global_load_dword v160, v[0:1], off offset:576
	global_load_dword v159, v[0:1], off offset:640
	global_load_dword v155, v[0:1], off offset:704
	s_cselect_b32 s13, s40, s18
	s_ashr_i32 s9, s8, 31
	s_lshl_b64 s[24:25], s[8:9], 19
	s_add_u32 s42, s16, s24
	s_addc_u32 s43, s17, s25
	s_and_b64 s[24:25], vcc, exec
	s_cselect_b32 s9, s43, s15
	s_cselect_b32 s24, s42, s14
	s_add_u32 s30, s18, 0x40080
	s_addc_u32 s31, s19, 0
	s_add_u32 s25, s14, 0x100
	v_mov_b32_e32 v8, 0
	s_addc_u32 s47, s15, 0
	s_mov_b32 s92, -2
	v_mov_b32_e32 v9, v8
	v_mov_b32_e32 v10, v8
	v_mov_b32_e32 v11, v8
	v_mov_b32_e32 v12, v8
	v_mov_b32_e32 v13, v8
	v_mov_b32_e32 v14, v8
	v_mov_b32_e32 v15, v8
	v_mov_b32_e32 v24, v8
	v_mov_b32_e32 v25, v8
	v_mov_b32_e32 v26, v8
	v_mov_b32_e32 v27, v8
	v_mov_b32_e32 v28, v8
	v_mov_b32_e32 v29, v8
	v_mov_b32_e32 v30, v8
	v_mov_b32_e32 v31, v8
	v_mov_b32_e32 v40, v8
	v_mov_b32_e32 v41, v8
	v_mov_b32_e32 v42, v8
	v_mov_b32_e32 v43, v8
	v_mov_b32_e32 v44, v8
	v_mov_b32_e32 v45, v8
	v_mov_b32_e32 v46, v8
	v_mov_b32_e32 v47, v8
	v_mov_b32_e32 v56, v8
	v_mov_b32_e32 v57, v8
	v_mov_b32_e32 v58, v8
	v_mov_b32_e32 v59, v8
	v_mov_b32_e32 v60, v8
	v_mov_b32_e32 v61, v8
	v_mov_b32_e32 v62, v8
	v_mov_b32_e32 v63, v8
	v_mov_b32_e32 v0, v8
	v_mov_b32_e32 v1, v8
	v_mov_b32_e32 v2, v8
	v_mov_b32_e32 v3, v8
	v_mov_b32_e32 v4, v8
	v_mov_b32_e32 v5, v8
	v_mov_b32_e32 v6, v8
	v_mov_b32_e32 v7, v8
	v_mov_b32_e32 v16, v8
	v_mov_b32_e32 v17, v8
	v_mov_b32_e32 v18, v8
	v_mov_b32_e32 v19, v8
	v_mov_b32_e32 v20, v8
	v_mov_b32_e32 v21, v8
	v_mov_b32_e32 v22, v8
	v_mov_b32_e32 v23, v8
	v_mov_b32_e32 v32, v8
	v_mov_b32_e32 v33, v8
	v_mov_b32_e32 v34, v8
	v_mov_b32_e32 v35, v8
	v_mov_b32_e32 v36, v8
	v_mov_b32_e32 v37, v8
	v_mov_b32_e32 v38, v8
	v_mov_b32_e32 v39, v8
	v_mov_b32_e32 v48, v8
	v_mov_b32_e32 v49, v8
	v_mov_b32_e32 v50, v8
	v_mov_b32_e32 v51, v8
	v_mov_b32_e32 v52, v8
	v_mov_b32_e32 v53, v8
	v_mov_b32_e32 v54, v8
	v_mov_b32_e32 v55, v8
	v_mov_b32_e32 v72, v8
	v_mov_b32_e32 v73, v8
	v_mov_b32_e32 v74, v8
	v_mov_b32_e32 v75, v8
	v_mov_b32_e32 v76, v8
	v_mov_b32_e32 v77, v8
	v_mov_b32_e32 v78, v8
	v_mov_b32_e32 v79, v8
	v_mov_b32_e32 v88, v8
	v_mov_b32_e32 v89, v8
	v_mov_b32_e32 v90, v8
	v_mov_b32_e32 v91, v8
	v_mov_b32_e32 v92, v8
	v_mov_b32_e32 v93, v8
	v_mov_b32_e32 v94, v8
	v_mov_b32_e32 v95, v8
	v_mov_b32_e32 v104, v8
	v_mov_b32_e32 v105, v8
	v_mov_b32_e32 v106, v8
	v_mov_b32_e32 v107, v8
	v_mov_b32_e32 v108, v8
	v_mov_b32_e32 v109, v8
	v_mov_b32_e32 v110, v8
	v_mov_b32_e32 v111, v8
	v_mov_b32_e32 v120, v8
	v_mov_b32_e32 v121, v8
	v_mov_b32_e32 v122, v8
	v_mov_b32_e32 v123, v8
	v_mov_b32_e32 v124, v8
	v_mov_b32_e32 v125, v8
	v_mov_b32_e32 v126, v8
	v_mov_b32_e32 v127, v8
	v_mov_b32_e32 v64, v8
	v_mov_b32_e32 v65, v8
	v_mov_b32_e32 v66, v8
	v_mov_b32_e32 v67, v8
	v_mov_b32_e32 v68, v8
	v_mov_b32_e32 v69, v8
	v_mov_b32_e32 v70, v8
	v_mov_b32_e32 v71, v8
	v_mov_b32_e32 v80, v8
	v_mov_b32_e32 v81, v8
	v_mov_b32_e32 v82, v8
	v_mov_b32_e32 v83, v8
	v_mov_b32_e32 v84, v8
	v_mov_b32_e32 v85, v8
	v_mov_b32_e32 v86, v8
	v_mov_b32_e32 v87, v8
	v_mov_b32_e32 v96, v8
	v_mov_b32_e32 v97, v8
	v_mov_b32_e32 v98, v8
	v_mov_b32_e32 v99, v8
	v_mov_b32_e32 v100, v8
	v_mov_b32_e32 v101, v8
	v_mov_b32_e32 v102, v8
	v_mov_b32_e32 v103, v8
	v_mov_b32_e32 v112, v8
	v_mov_b32_e32 v113, v8
	v_mov_b32_e32 v114, v8
	v_mov_b32_e32 v115, v8
	v_mov_b32_e32 v116, v8
	v_mov_b32_e32 v117, v8
	v_mov_b32_e32 v118, v8
	v_mov_b32_e32 v119, v8
	s_cmpk_gt_u32 s4, 0xff
	s_cbranch_scc0 .Lg1_enter
	s_barrier
.Lg1_enter:
.LBB0_391:
	s_add_u32 s14, s30, 0xfffc0080
	s_addc_u32 s15, s31, -1
	s_add_i32 s20, 16, 0x10000
	v_add_u32_e32 v130, s20, v156
	ds_read_b128 v[166:169], v130
	ds_read_b128 v[170:173], v130 offset:1024
	ds_read_b128 v[174:177], v130 offset:2048
	ds_read_b128 v[178:181], v130 offset:3072
	s_cmp_eq_u32 s92, 12
	s_cselect_b32 s19, s1, s15
	s_cselect_b32 s18, s13, s14
	s_cselect_b32 s15, s9, s47
	s_cselect_b32 s14, s24, s25
	v_lshl_add_u64 v[130:131], s[30:31], 0, v[150:151]
	s_add_i32 m0, s34, 0xc000
	ds_read_b128 v[182:185], v158
	ds_read_b128 v[186:189], v158 offset:1024
	ds_read_b128 v[190:193], v158 offset:2048
	ds_read_b128 v[194:197], v158 offset:3072
	ds_read_b128 v[198:201], v158 offset:4096
	ds_read_b128 v[202:205], v158 offset:5120
	ds_read_b128 v[206:209], v158 offset:6144
	ds_read_b128 v[210:213], v158 offset:7168
	global_load_lds_dwordx4 v[130:131], off
	v_lshl_add_u64 v[130:131], s[30:31], 0, v[152:153]
	s_add_i32 m0, s34, 0xe000
	s_nop 0
	global_load_lds_dwordx4 v[130:131], off
	s_add_i32 s50, 16, 0x14000
	v_add_u32_e32 v130, s50, v156
	ds_read_b128 v[214:217], v130
	ds_read_b128 v[218:221], v130 offset:1024
	ds_read_b128 v[222:225], v130 offset:2048
	ds_read_b128 v[226:229], v130 offset:3072
	s_waitcnt vmcnt(8) lgkmcnt(0)
	s_barrier
	v_mfma_f32_16x16x32_bf16 v[116:119], v[166:169], v[182:185], v[116:119]
	v_mfma_f32_16x16x32_bf16 v[112:115], v[174:177], v[182:185], v[112:115]
	v_mfma_f32_16x16x32_bf16 v[100:103], v[166:169], v[190:193], v[100:103]
	v_mfma_f32_16x16x32_bf16 v[96:99], v[174:177], v[190:193], v[96:99]
	v_mfma_f32_16x16x32_bf16 v[84:87], v[166:169], v[198:201], v[84:87]
	v_mfma_f32_16x16x32_bf16 v[80:83], v[174:177], v[198:201], v[80:83]
	v_mfma_f32_16x16x32_bf16 v[68:71], v[166:169], v[206:209], v[68:71]
	v_mfma_f32_16x16x32_bf16 v[64:67], v[174:177], v[206:209], v[64:67]
	v_mfma_f32_16x16x32_bf16 v[116:119], v[170:173], v[186:189], v[116:119]
	v_mfma_f32_16x16x32_bf16 v[112:115], v[178:181], v[186:189], v[112:115]
	v_mfma_f32_16x16x32_bf16 v[100:103], v[170:173], v[194:197], v[100:103]
	v_mfma_f32_16x16x32_bf16 v[96:99], v[178:181], v[194:197], v[96:99]
	v_mfma_f32_16x16x32_bf16 v[84:87], v[170:173], v[202:205], v[84:87]
	v_mfma_f32_16x16x32_bf16 v[80:83], v[178:181], v[202:205], v[80:83]
	v_mfma_f32_16x16x32_bf16 v[68:71], v[170:173], v[210:213], v[68:71]
	v_mfma_f32_16x16x32_bf16 v[64:67], v[178:181], v[210:213], v[64:67]
	v_mfma_f32_16x16x32_bf16 v[124:127], v[214:217], v[182:185], v[124:127]
	v_mfma_f32_16x16x32_bf16 v[120:123], v[222:225], v[182:185], v[120:123]
	v_mfma_f32_16x16x32_bf16 v[108:111], v[214:217], v[190:193], v[108:111]
	v_mfma_f32_16x16x32_bf16 v[104:107], v[222:225], v[190:193], v[104:107]
	v_mfma_f32_16x16x32_bf16 v[92:95], v[214:217], v[198:201], v[92:95]
	v_mfma_f32_16x16x32_bf16 v[88:91], v[222:225], v[198:201], v[88:91]
	v_mfma_f32_16x16x32_bf16 v[76:79], v[214:217], v[206:209], v[76:79]
	v_mfma_f32_16x16x32_bf16 v[72:75], v[222:225], v[206:209], v[72:75]
	v_mfma_f32_16x16x32_bf16 v[124:127], v[218:221], v[186:189], v[124:127]
	v_mfma_f32_16x16x32_bf16 v[120:123], v[226:229], v[186:189], v[120:123]
	v_mfma_f32_16x16x32_bf16 v[108:111], v[218:221], v[194:197], v[108:111]
	v_mfma_f32_16x16x32_bf16 v[104:107], v[226:229], v[194:197], v[104:107]
	v_mfma_f32_16x16x32_bf16 v[92:95], v[218:221], v[202:205], v[92:95]
	v_mfma_f32_16x16x32_bf16 v[88:91], v[226:229], v[202:205], v[88:91]
	v_mfma_f32_16x16x32_bf16 v[76:79], v[218:221], v[210:213], v[76:79]
	v_mfma_f32_16x16x32_bf16 v[72:75], v[226:229], v[210:213], v[72:75]
	s_barrier
	ds_read_b128 v[182:185], v158 offset:16384
	ds_read_b128 v[186:189], v158 offset:17408
	ds_read_b128 v[190:193], v158 offset:18432
	ds_read_b128 v[194:197], v158 offset:19456
	ds_read_b128 v[198:201], v158 offset:20480
	ds_read_b128 v[202:205], v158 offset:21504
	ds_read_b128 v[206:209], v158 offset:22528
	ds_read_b128 v[210:213], v158 offset:23552
	s_add_i32 s20, s20, s5
	v_lshl_add_u64 v[130:131], s[14:15], 0, v[128:129]
	s_mov_b32 m0, s20
	v_lshl_add_u64 v[132:133], s[14:15], 0, v[144:145]
	global_load_lds_dwordx4 v[130:131], off
	s_add_i32 m0, s20, 0x2000
	s_nop 0
	global_load_lds_dwordx4 v[132:133], off
	s_mov_b32 m0, s34
	v_lshl_add_u64 v[134:135], s[18:19], 0, v[148:149]
	global_load_lds_dwordx4 v[134:135], off
	v_lshl_add_u64 v[136:137], s[18:19], 0, v[146:147]
	s_mov_b32 m0, s35
	s_nop 0
	global_load_lds_dwordx4 v[136:137], off
	s_add_u32 s48, s14, 0x40000
	s_addc_u32 s49, s15, 0
	s_add_i32 s20, s50, s5
	v_lshl_add_u64 v[138:139], s[48:49], 0, v[128:129]
	s_mov_b32 m0, s20
	s_nop 0
	global_load_lds_dwordx4 v[138:139], off
	v_lshl_add_u64 v[138:139], s[48:49], 0, v[144:145]
	s_add_i32 m0, s20, 0x2000
	s_nop 0
	global_load_lds_dwordx4 v[138:139], off
	s_waitcnt vmcnt(8) lgkmcnt(0)
	s_barrier
	v_mfma_f32_16x16x32_bf16 v[52:55], v[166:169], v[182:185], v[52:55]
	v_mfma_f32_16x16x32_bf16 v[48:51], v[174:177], v[182:185], v[48:51]
	v_mfma_f32_16x16x32_bf16 v[36:39], v[166:169], v[190:193], v[36:39]
	v_mfma_f32_16x16x32_bf16 v[32:35], v[174:177], v[190:193], v[32:35]
	v_mfma_f32_16x16x32_bf16 v[20:23], v[166:169], v[198:201], v[20:23]
	v_mfma_f32_16x16x32_bf16 v[16:19], v[174:177], v[198:201], v[16:19]
	v_mfma_f32_16x16x32_bf16 v[4:7], v[166:169], v[206:209], v[4:7]
	v_mfma_f32_16x16x32_bf16 v[0:3], v[174:177], v[206:209], v[0:3]
	v_mfma_f32_16x16x32_bf16 v[52:55], v[170:173], v[186:189], v[52:55]
	v_mfma_f32_16x16x32_bf16 v[48:51], v[178:181], v[186:189], v[48:51]
	v_mfma_f32_16x16x32_bf16 v[36:39], v[170:173], v[194:197], v[36:39]
	v_mfma_f32_16x16x32_bf16 v[32:35], v[178:181], v[194:197], v[32:35]
	v_mfma_f32_16x16x32_bf16 v[20:23], v[170:173], v[202:205], v[20:23]
	v_mfma_f32_16x16x32_bf16 v[16:19], v[178:181], v[202:205], v[16:19]
	v_mfma_f32_16x16x32_bf16 v[4:7], v[170:173], v[210:213], v[4:7]
	v_mfma_f32_16x16x32_bf16 v[0:3], v[178:181], v[210:213], v[0:3]
	v_mfma_f32_16x16x32_bf16 v[60:63], v[214:217], v[182:185], v[60:63]
	v_mfma_f32_16x16x32_bf16 v[56:59], v[222:225], v[182:185], v[56:59]
	v_mfma_f32_16x16x32_bf16 v[44:47], v[214:217], v[190:193], v[44:47]
	v_mfma_f32_16x16x32_bf16 v[40:43], v[222:225], v[190:193], v[40:43]
	v_mfma_f32_16x16x32_bf16 v[28:31], v[214:217], v[198:201], v[28:31]
	v_mfma_f32_16x16x32_bf16 v[24:27], v[222:225], v[198:201], v[24:27]
	v_mfma_f32_16x16x32_bf16 v[12:15], v[214:217], v[206:209], v[12:15]
	v_mfma_f32_16x16x32_bf16 v[8:11], v[222:225], v[206:209], v[8:11]
	v_mfma_f32_16x16x32_bf16 v[60:63], v[218:221], v[186:189], v[60:63]
	v_mfma_f32_16x16x32_bf16 v[56:59], v[226:229], v[186:189], v[56:59]
	v_mfma_f32_16x16x32_bf16 v[44:47], v[218:221], v[194:197], v[44:47]
	v_mfma_f32_16x16x32_bf16 v[40:43], v[226:229], v[194:197], v[40:43]
	v_mfma_f32_16x16x32_bf16 v[28:31], v[218:221], v[202:205], v[28:31]
	v_mfma_f32_16x16x32_bf16 v[24:27], v[226:229], v[202:205], v[24:27]
	v_mfma_f32_16x16x32_bf16 v[12:15], v[218:221], v[210:213], v[12:15]
	v_mfma_f32_16x16x32_bf16 v[8:11], v[226:229], v[210:213], v[8:11]
	s_add_i32 s20, 16, 0x18000
	v_add_u32_e32 v138, s20, v156
	s_barrier
	ds_read_b128 v[166:169], v138
	ds_read_b128 v[170:173], v138 offset:1024
	ds_read_b128 v[174:177], v138 offset:2048
	ds_read_b128 v[178:181], v138 offset:3072
	s_add_u32 s18, s18, 0x40000
	s_addc_u32 s19, s19, 0
	s_mov_b32 m0, s36
	v_lshl_add_u64 v[214:215], s[18:19], 0, v[148:149]
	ds_read_b128 v[182:185], v158 offset:32768
	ds_read_b128 v[186:189], v158 offset:33792
	ds_read_b128 v[190:193], v158 offset:34816
	ds_read_b128 v[194:197], v158 offset:35840
	ds_read_b128 v[198:201], v158 offset:36864
	ds_read_b128 v[202:205], v158 offset:37888
	ds_read_b128 v[206:209], v158 offset:38912
	ds_read_b128 v[210:213], v158 offset:39936
	global_load_lds_dwordx4 v[214:215], off
	v_lshl_add_u64 v[214:215], s[18:19], 0, v[146:147]
	s_mov_b32 m0, s37
	s_nop 0
	global_load_lds_dwordx4 v[214:215], off
	s_add_i32 s18, 16, 0x1c000
	v_add_u32_e32 v138, s18, v156
	ds_read_b128 v[214:217], v138
	ds_read_b128 v[218:221], v138 offset:1024
	ds_read_b128 v[222:225], v138 offset:2048
	ds_read_b128 v[226:229], v138 offset:3072
	s_waitcnt vmcnt(8) lgkmcnt(0)
	s_barrier
	v_mfma_f32_16x16x32_bf16 v[116:119], v[166:169], v[182:185], v[116:119]
	v_mfma_f32_16x16x32_bf16 v[112:115], v[174:177], v[182:185], v[112:115]
	v_mfma_f32_16x16x32_bf16 v[100:103], v[166:169], v[190:193], v[100:103]
	v_mfma_f32_16x16x32_bf16 v[96:99], v[174:177], v[190:193], v[96:99]
	v_mfma_f32_16x16x32_bf16 v[84:87], v[166:169], v[198:201], v[84:87]
	v_mfma_f32_16x16x32_bf16 v[80:83], v[174:177], v[198:201], v[80:83]
	v_mfma_f32_16x16x32_bf16 v[68:71], v[166:169], v[206:209], v[68:71]
	v_mfma_f32_16x16x32_bf16 v[64:67], v[174:177], v[206:209], v[64:67]
	v_mfma_f32_16x16x32_bf16 v[116:119], v[170:173], v[186:189], v[116:119]
	v_mfma_f32_16x16x32_bf16 v[112:115], v[178:181], v[186:189], v[112:115]
	v_mfma_f32_16x16x32_bf16 v[100:103], v[170:173], v[194:197], v[100:103]
	v_mfma_f32_16x16x32_bf16 v[96:99], v[178:181], v[194:197], v[96:99]
	v_mfma_f32_16x16x32_bf16 v[84:87], v[170:173], v[202:205], v[84:87]
	v_mfma_f32_16x16x32_bf16 v[80:83], v[178:181], v[202:205], v[80:83]
	v_mfma_f32_16x16x32_bf16 v[68:71], v[170:173], v[210:213], v[68:71]
	v_mfma_f32_16x16x32_bf16 v[64:67], v[178:181], v[210:213], v[64:67]
	v_mfma_f32_16x16x32_bf16 v[124:127], v[214:217], v[182:185], v[124:127]
	v_mfma_f32_16x16x32_bf16 v[120:123], v[222:225], v[182:185], v[120:123]
	v_mfma_f32_16x16x32_bf16 v[108:111], v[214:217], v[190:193], v[108:111]
	v_mfma_f32_16x16x32_bf16 v[104:107], v[222:225], v[190:193], v[104:107]
	v_mfma_f32_16x16x32_bf16 v[92:95], v[214:217], v[198:201], v[92:95]
	v_mfma_f32_16x16x32_bf16 v[88:91], v[222:225], v[198:201], v[88:91]
	v_mfma_f32_16x16x32_bf16 v[76:79], v[214:217], v[206:209], v[76:79]
	v_mfma_f32_16x16x32_bf16 v[72:75], v[222:225], v[206:209], v[72:75]
	v_mfma_f32_16x16x32_bf16 v[124:127], v[218:221], v[186:189], v[124:127]
	v_mfma_f32_16x16x32_bf16 v[120:123], v[226:229], v[186:189], v[120:123]
	v_mfma_f32_16x16x32_bf16 v[108:111], v[218:221], v[194:197], v[108:111]
	v_mfma_f32_16x16x32_bf16 v[104:107], v[226:229], v[194:197], v[104:107]
	v_mfma_f32_16x16x32_bf16 v[92:95], v[218:221], v[202:205], v[92:95]
	v_mfma_f32_16x16x32_bf16 v[88:91], v[226:229], v[202:205], v[88:91]
	v_mfma_f32_16x16x32_bf16 v[76:79], v[218:221], v[210:213], v[76:79]
	v_mfma_f32_16x16x32_bf16 v[72:75], v[226:229], v[210:213], v[72:75]
	s_barrier
	ds_read_b128 v[182:185], v158 offset:49152
	ds_read_b128 v[186:189], v158 offset:50176
	ds_read_b128 v[190:193], v158 offset:51200
	ds_read_b128 v[194:197], v158 offset:52224
	ds_read_b128 v[198:201], v158 offset:53248
	ds_read_b128 v[202:205], v158 offset:54272
	ds_read_b128 v[206:209], v158 offset:55296
	ds_read_b128 v[210:213], v158 offset:56320
	s_add_i32 s19, s20, s5
	v_lshl_add_u64 v[130:131], v[130:131], 0, s[28:29]
	s_mov_b32 m0, s19
	s_nop 0
	global_load_lds_dwordx4 v[130:131], off
	v_lshl_add_u64 v[130:131], v[132:133], 0, s[28:29]
	s_add_i32 m0, s19, 0x2000
	s_nop 0
	global_load_lds_dwordx4 v[130:131], off
	s_mov_b32 m0, s44
	v_lshl_add_u64 v[130:131], v[134:135], 0, s[28:29]
	global_load_lds_dwordx4 v[130:131], off
	v_lshl_add_u64 v[130:131], v[136:137], 0, s[28:29]
	s_mov_b32 m0, s45
	s_nop 0
	global_load_lds_dwordx4 v[130:131], off
	s_add_u32 s14, s14, 0x40080
	s_addc_u32 s15, s15, 0
	s_add_i32 s18, s18, s5
	v_lshl_add_u64 v[130:131], s[14:15], 0, v[128:129]
	s_mov_b32 m0, s18
	s_nop 0
	global_load_lds_dwordx4 v[130:131], off
	v_lshl_add_u64 v[130:131], s[14:15], 0, v[144:145]
	s_add_i32 m0, s18, 0x2000
	s_nop 0
	global_load_lds_dwordx4 v[130:131], off
	s_waitcnt vmcnt(8) lgkmcnt(0)
	s_barrier
	v_mfma_f32_16x16x32_bf16 v[52:55], v[166:169], v[182:185], v[52:55]
	v_mfma_f32_16x16x32_bf16 v[48:51], v[174:177], v[182:185], v[48:51]
	v_mfma_f32_16x16x32_bf16 v[36:39], v[166:169], v[190:193], v[36:39]
	v_mfma_f32_16x16x32_bf16 v[32:35], v[174:177], v[190:193], v[32:35]
	v_mfma_f32_16x16x32_bf16 v[20:23], v[166:169], v[198:201], v[20:23]
	v_mfma_f32_16x16x32_bf16 v[16:19], v[174:177], v[198:201], v[16:19]
	v_mfma_f32_16x16x32_bf16 v[4:7], v[166:169], v[206:209], v[4:7]
	v_mfma_f32_16x16x32_bf16 v[0:3], v[174:177], v[206:209], v[0:3]
	v_mfma_f32_16x16x32_bf16 v[52:55], v[170:173], v[186:189], v[52:55]
	v_mfma_f32_16x16x32_bf16 v[48:51], v[178:181], v[186:189], v[48:51]
	v_mfma_f32_16x16x32_bf16 v[36:39], v[170:173], v[194:197], v[36:39]
	v_mfma_f32_16x16x32_bf16 v[32:35], v[178:181], v[194:197], v[32:35]
	v_mfma_f32_16x16x32_bf16 v[20:23], v[170:173], v[202:205], v[20:23]
	v_mfma_f32_16x16x32_bf16 v[16:19], v[178:181], v[202:205], v[16:19]
	v_mfma_f32_16x16x32_bf16 v[4:7], v[170:173], v[210:213], v[4:7]
	v_mfma_f32_16x16x32_bf16 v[0:3], v[178:181], v[210:213], v[0:3]
	v_mfma_f32_16x16x32_bf16 v[60:63], v[214:217], v[182:185], v[60:63]
	v_mfma_f32_16x16x32_bf16 v[56:59], v[222:225], v[182:185], v[56:59]
	v_mfma_f32_16x16x32_bf16 v[44:47], v[214:217], v[190:193], v[44:47]
	v_mfma_f32_16x16x32_bf16 v[40:43], v[222:225], v[190:193], v[40:43]
	v_mfma_f32_16x16x32_bf16 v[28:31], v[214:217], v[198:201], v[28:31]
	v_mfma_f32_16x16x32_bf16 v[24:27], v[222:225], v[198:201], v[24:27]
	v_mfma_f32_16x16x32_bf16 v[12:15], v[214:217], v[206:209], v[12:15]
	v_mfma_f32_16x16x32_bf16 v[8:11], v[222:225], v[206:209], v[8:11]
	v_mfma_f32_16x16x32_bf16 v[60:63], v[218:221], v[186:189], v[60:63]
	v_mfma_f32_16x16x32_bf16 v[56:59], v[226:229], v[186:189], v[56:59]
	v_mfma_f32_16x16x32_bf16 v[44:47], v[218:221], v[194:197], v[44:47]
	v_mfma_f32_16x16x32_bf16 v[40:43], v[226:229], v[194:197], v[40:43]
	v_mfma_f32_16x16x32_bf16 v[28:31], v[218:221], v[202:205], v[28:31]
	v_mfma_f32_16x16x32_bf16 v[24:27], v[226:229], v[202:205], v[24:27]
	v_mfma_f32_16x16x32_bf16 v[12:15], v[218:221], v[210:213], v[12:15]
	v_mfma_f32_16x16x32_bf16 v[8:11], v[226:229], v[210:213], v[8:11]
	s_add_i32 s92, s92, 2
	s_add_u32 s30, s30, 0x100
	s_addc_u32 s31, s31, 0
	s_add_u32 s25, s25, 0x100
	s_addc_u32 s47, s47, 0
	s_cmp_gt_u32 s92, 13
	s_cbranch_scc1 .Lg1_exit
	s_barrier
	s_branch .LBB0_391

.Lg1_epi:
	s_nop 0
	s_nop 0
	s_nop 0
	s_nop 0
	s_nop 0
	s_nop 0
	s_nop 0
	s_nop 0
	s_waitcnt vmcnt(0)
	v_fmamk_f32 v132, v165, 0x3a800000, v235
	v_cmp_gt_f32_e32 vcc, s86, v132
	v_mul_f32_e32 v133, 0x4b800000, v132
	v_pk_mul_f32 v[126:127], v[118:119], v[126:127]
	v_cndmask_b32_e32 v132, v132, v133, vcc
	v_rsq_f32_e32 v132, v132
	v_pk_mul_f32 v[122:123], v[114:115], v[122:123]
	v_lshl_or_b32 v130, s0, 7, v157
	v_ashrrev_i32_e32 v131, 31, v130
	v_mul_f32_e32 v133, 0x45800000, v132
	v_cndmask_b32_e32 v132, v132, v133, vcc
	v_mul_f32_e32 v133, 0xbfb8aa3b, v132
	v_mul_f32_e32 v135, v133, v112
	v_exp_f32_e32 v135, v135
	v_mul_f32_e32 v134, v133, v116
	v_exp_f32_e32 v134, v134
	v_mul_f32_e32 v132, v132, v132
	v_add_f32_e32 v135, 1.0, v135
	v_rcp_f32_e32 v136, v135
	v_mul_f32_e32 v135, v133, v117
	v_exp_f32_e32 v135, v135
	v_add_f32_e32 v134, 1.0, v134
	v_rcp_f32_e32 v134, v134
	v_pk_mul_f32 v[116:117], v[116:117], v[124:125]
	v_add_f32_e32 v135, 1.0, v135
	v_rcp_f32_e32 v135, v135
	v_mul_f32_e32 v118, v133, v118
	v_mul_f32_e32 v119, v133, v119
	v_exp_f32_e32 v118, v118
	v_pk_mul_f32 v[124:125], v[132:133], v[134:135] op_sel_hi:[0,1]
	v_pk_mul_f32 v[116:117], v[124:125], v[116:117]
	v_mul_f32_e32 v124, v133, v113
	v_exp_f32_e32 v124, v124
	v_mul_f32_e32 v114, v133, v114
	v_exp_f32_e32 v119, v119
	v_mul_f32_e32 v115, v133, v115
	v_exp_f32_e32 v114, v114
	v_exp_f32_e32 v115, v115
	v_add_f32_e32 v124, 1.0, v124
	v_add_f32_e32 v118, 1.0, v118
	v_add_f32_e32 v119, 1.0, v119
	v_rcp_f32_e32 v137, v124
	v_rcp_f32_e32 v118, v118
	v_add_f32_e32 v114, 1.0, v114
	v_rcp_f32_e32 v119, v119
	v_add_f32_e32 v115, 1.0, v115
	v_rcp_f32_e32 v114, v114
	v_rcp_f32_e32 v115, v115
	v_pk_mul_f32 v[112:113], v[112:113], v[120:121]
	v_pk_mul_f32 v[120:121], v[132:133], v[136:137] op_sel_hi:[0,1]
	v_pk_mul_f32 v[118:119], v[132:133], v[118:119] op_sel_hi:[0,1]
	v_pk_mul_f32 v[112:113], v[120:121], v[112:113]
	v_pk_mul_f32 v[118:119], v[118:119], v[126:127]
	v_pk_mul_f32 v[114:115], v[132:133], v[114:115] op_sel_hi:[0,1]
	v_pk_mul_f32 v[114:115], v[114:115], v[122:123]
	v_cvt_pk_bf16_f32 v116, v116, v117
	v_cvt_pk_bf16_f32 v117, v118, v119
	v_cvt_pk_bf16_f32 v118, v112, v113
	v_mov_b64_e32 v[112:113], s[94:95]
	s_movk_i32 s9, 0x1600
	v_cvt_pk_bf16_f32 v119, v114, v115
	v_mad_i64_i32 v[120:121], s[0:1], v154, s9, v[112:113]
	v_lshlrev_b64 v[114:115], 1, v[130:131]
	v_lshl_add_u64 v[120:121], v[120:121], 0, v[114:115]
	global_store_dwordx4 v[120:121], v[116:119], off nt
	v_pk_mul_f32 v[106:107], v[98:99], v[106:107]
	v_pk_mul_f32 v[110:111], v[102:103], v[110:111]
	v_fmamk_f32 v116, v164, 0x3a800000, v235
	v_cmp_gt_f32_e32 vcc, s86, v116
	v_mul_f32_e32 v117, 0x4b800000, v116
	v_pk_mul_f32 v[90:91], v[82:83], v[90:91]
	v_cndmask_b32_e32 v116, v116, v117, vcc
	v_rsq_f32_e32 v116, v116
	v_pk_mul_f32 v[94:95], v[86:87], v[94:95]
	v_pk_mul_f32 v[74:75], v[66:67], v[74:75]
	v_pk_mul_f32 v[78:79], v[70:71], v[78:79]
	v_mul_f32_e32 v117, 0x45800000, v116
	v_cndmask_b32_e32 v116, v116, v117, vcc
	v_mul_f32_e32 v117, 0xbfb8aa3b, v116
	v_mul_f32_e32 v119, v117, v96
	v_exp_f32_e32 v119, v119
	v_mul_f32_e32 v118, v117, v100
	v_exp_f32_e32 v118, v118
	v_mul_f32_e32 v116, v116, v116
	v_add_f32_e32 v119, 1.0, v119
	v_rcp_f32_e32 v120, v119
	v_mul_f32_e32 v119, v117, v101
	v_exp_f32_e32 v119, v119
	v_add_f32_e32 v118, 1.0, v118
	v_rcp_f32_e32 v118, v118
	v_pk_mul_f32 v[100:101], v[100:101], v[108:109]
	v_add_f32_e32 v119, 1.0, v119
	v_rcp_f32_e32 v119, v119
	v_pk_mul_f32 v[58:59], v[50:51], v[58:59]
	v_pk_mul_f32 v[62:63], v[54:55], v[62:63]
	v_pk_mul_f32 v[42:43], v[34:35], v[42:43]
	v_pk_mul_f32 v[108:109], v[116:117], v[118:119] op_sel_hi:[0,1]
	v_pk_mul_f32 v[100:101], v[108:109], v[100:101]
	v_mul_f32_e32 v108, v117, v97
	v_exp_f32_e32 v108, v108
	v_pk_mul_f32 v[96:97], v[96:97], v[104:105]
	v_pk_mul_f32 v[46:47], v[38:39], v[46:47]
	v_pk_mul_f32 v[26:27], v[18:19], v[26:27]
	v_add_f32_e32 v108, 1.0, v108
	v_rcp_f32_e32 v121, v108
	v_or_b32_e32 v108, 16, v154
	v_pk_mul_f32 v[30:31], v[22:23], v[30:31]
	v_pk_mul_f32 v[10:11], v[2:3], v[10:11]
	v_pk_mul_f32 v[104:105], v[116:117], v[120:121] op_sel_hi:[0,1]
	v_pk_mul_f32 v[104:105], v[104:105], v[96:97]
	v_mul_f32_e32 v97, v117, v98
	v_exp_f32_e32 v97, v97
	v_mul_f32_e32 v96, v117, v102
	v_exp_f32_e32 v96, v96
	v_pk_mul_f32 v[14:15], v[6:7], v[14:15]
	v_add_f32_e32 v97, 1.0, v97
	v_rcp_f32_e32 v98, v97
	v_mul_f32_e32 v97, v117, v103
	v_exp_f32_e32 v97, v97
	v_add_f32_e32 v96, 1.0, v96
	v_rcp_f32_e32 v96, v96
	s_mov_b32 s20, s12
	v_add_f32_e32 v97, 1.0, v97
	v_rcp_f32_e32 v97, v97
	s_mov_b64 s[14:15], s[42:43]
	s_mov_b64 s[18:19], s[40:41]
	v_pk_mul_f32 v[96:97], v[116:117], v[96:97] op_sel_hi:[0,1]
	v_pk_mul_f32 v[102:103], v[96:97], v[110:111]
	v_mul_f32_e32 v96, v117, v99
	v_exp_f32_e32 v96, v96
	s_nop 0
	v_add_f32_e32 v96, 1.0, v96
	v_rcp_f32_e32 v99, v96
	s_nop 0
	v_pk_mul_f32 v[96:97], v[116:117], v[98:99] op_sel_hi:[0,1]
	v_pk_mul_f32 v[106:107], v[96:97], v[106:107]
	v_cvt_pk_bf16_f32 v96, v100, v101
	v_mad_i64_i32 v[100:101], s[0:1], v108, s9, v[112:113]
	v_cvt_pk_bf16_f32 v97, v102, v103
	v_cvt_pk_bf16_f32 v98, v104, v105
	v_cvt_pk_bf16_f32 v99, v106, v107
	v_lshl_add_u64 v[100:101], v[100:101], 0, v[114:115]
	global_store_dwordx4 v[100:101], v[96:99], off nt
	s_nop 1
	v_fmamk_f32 v96, v163, 0x3a800000, v235
	v_cmp_gt_f32_e32 vcc, s86, v96
	v_mul_f32_e32 v97, 0x4b800000, v96
	s_nop 0
	v_cndmask_b32_e32 v96, v96, v97, vcc
	v_rsq_f32_e32 v96, v96
	s_nop 0
	v_mul_f32_e32 v97, 0x45800000, v96
	v_cndmask_b32_e32 v96, v96, v97, vcc
	v_mul_f32_e32 v97, 0xbfb8aa3b, v96
	v_mul_f32_e32 v99, v97, v80
	v_exp_f32_e32 v99, v99
	v_mul_f32_e32 v98, v97, v84
	v_exp_f32_e32 v98, v98
	v_mul_f32_e32 v96, v96, v96
	v_add_f32_e32 v99, 1.0, v99
	v_rcp_f32_e32 v100, v99
	v_mul_f32_e32 v99, v97, v85
	v_exp_f32_e32 v99, v99
	v_add_f32_e32 v98, 1.0, v98
	v_rcp_f32_e32 v98, v98
	v_pk_mul_f32 v[84:85], v[84:85], v[92:93]
	v_add_f32_e32 v99, 1.0, v99
	v_rcp_f32_e32 v99, v99
	s_nop 0
	v_pk_mul_f32 v[92:93], v[96:97], v[98:99] op_sel_hi:[0,1]
	v_pk_mul_f32 v[84:85], v[92:93], v[84:85]
	v_mul_f32_e32 v92, v97, v81
	v_exp_f32_e32 v92, v92
	v_pk_mul_f32 v[80:81], v[80:81], v[88:89]
	v_add_f32_e32 v92, 1.0, v92
	v_rcp_f32_e32 v101, v92
	v_or_b32_e32 v92, 32, v154
	v_pk_mul_f32 v[88:89], v[96:97], v[100:101] op_sel_hi:[0,1]
	v_pk_mul_f32 v[88:89], v[88:89], v[80:81]
	v_mul_f32_e32 v81, v97, v82
	v_exp_f32_e32 v81, v81
	v_mul_f32_e32 v80, v97, v86
	v_exp_f32_e32 v80, v80
	v_add_f32_e32 v81, 1.0, v81
	v_rcp_f32_e32 v82, v81
	v_mul_f32_e32 v81, v97, v87
	v_exp_f32_e32 v81, v81
	v_add_f32_e32 v80, 1.0, v80
	v_rcp_f32_e32 v80, v80
	v_add_f32_e32 v81, 1.0, v81
	v_rcp_f32_e32 v81, v81
	s_nop 0
	v_pk_mul_f32 v[80:81], v[96:97], v[80:81] op_sel_hi:[0,1]
	v_pk_mul_f32 v[86:87], v[80:81], v[94:95]
	v_mul_f32_e32 v80, v97, v83
	v_exp_f32_e32 v80, v80
	s_nop 0
	v_add_f32_e32 v80, 1.0, v80
	v_rcp_f32_e32 v83, v80
	s_nop 0
	v_pk_mul_f32 v[80:81], v[96:97], v[82:83] op_sel_hi:[0,1]
	v_pk_mul_f32 v[90:91], v[80:81], v[90:91]
	v_cvt_pk_bf16_f32 v80, v84, v85
	v_mad_i64_i32 v[84:85], s[0:1], v92, s9, v[112:113]
	v_cvt_pk_bf16_f32 v81, v86, v87
	v_cvt_pk_bf16_f32 v82, v88, v89
	v_cvt_pk_bf16_f32 v83, v90, v91
	v_lshl_add_u64 v[84:85], v[84:85], 0, v[114:115]
	global_store_dwordx4 v[84:85], v[80:83], off nt
	s_nop 1
	v_fmamk_f32 v80, v162, 0x3a800000, v235
	v_cmp_gt_f32_e32 vcc, s86, v80
	v_mul_f32_e32 v81, 0x4b800000, v80
	s_nop 0
	v_cndmask_b32_e32 v80, v80, v81, vcc
	v_rsq_f32_e32 v80, v80
	s_nop 0
	v_mul_f32_e32 v81, 0x45800000, v80
	v_cndmask_b32_e32 v80, v80, v81, vcc
	v_mul_f32_e32 v81, 0xbfb8aa3b, v80
	v_mul_f32_e32 v83, v81, v64
	v_exp_f32_e32 v83, v83
	v_mul_f32_e32 v82, v81, v68
	v_exp_f32_e32 v82, v82
	v_mul_f32_e32 v80, v80, v80
	v_add_f32_e32 v83, 1.0, v83
	v_rcp_f32_e32 v84, v83
	v_mul_f32_e32 v83, v81, v69
	v_exp_f32_e32 v83, v83
	v_add_f32_e32 v82, 1.0, v82
	v_rcp_f32_e32 v82, v82
	v_pk_mul_f32 v[68:69], v[68:69], v[76:77]
	v_add_f32_e32 v83, 1.0, v83
	v_rcp_f32_e32 v83, v83
	s_nop 0
	v_pk_mul_f32 v[76:77], v[80:81], v[82:83] op_sel_hi:[0,1]
	v_pk_mul_f32 v[68:69], v[76:77], v[68:69]
	v_mul_f32_e32 v76, v81, v65
	v_exp_f32_e32 v76, v76
	v_pk_mul_f32 v[64:65], v[64:65], v[72:73]
	v_add_f32_e32 v76, 1.0, v76
	v_rcp_f32_e32 v85, v76
	v_or_b32_e32 v76, 48, v154
	v_pk_mul_f32 v[72:73], v[80:81], v[84:85] op_sel_hi:[0,1]
	v_pk_mul_f32 v[72:73], v[72:73], v[64:65]
	v_mul_f32_e32 v65, v81, v66
	v_exp_f32_e32 v65, v65
	v_mul_f32_e32 v64, v81, v70
	v_exp_f32_e32 v64, v64
	v_add_f32_e32 v65, 1.0, v65
	v_rcp_f32_e32 v66, v65
	v_mul_f32_e32 v65, v81, v71
	v_exp_f32_e32 v65, v65
	v_add_f32_e32 v64, 1.0, v64
	v_rcp_f32_e32 v64, v64
	v_add_f32_e32 v65, 1.0, v65
	v_rcp_f32_e32 v65, v65
	s_nop 0
	v_pk_mul_f32 v[64:65], v[80:81], v[64:65] op_sel_hi:[0,1]
	v_pk_mul_f32 v[70:71], v[64:65], v[78:79]
	v_mul_f32_e32 v64, v81, v67
	v_exp_f32_e32 v64, v64
	s_nop 0
	v_add_f32_e32 v64, 1.0, v64
	v_rcp_f32_e32 v67, v64
	s_nop 0
	v_pk_mul_f32 v[64:65], v[80:81], v[66:67] op_sel_hi:[0,1]
	v_pk_mul_f32 v[74:75], v[64:65], v[74:75]
	v_cvt_pk_bf16_f32 v64, v68, v69
	v_mad_i64_i32 v[68:69], s[0:1], v76, s9, v[112:113]
	v_cvt_pk_bf16_f32 v65, v70, v71
	v_cvt_pk_bf16_f32 v66, v72, v73
	v_cvt_pk_bf16_f32 v67, v74, v75
	v_lshl_add_u64 v[68:69], v[68:69], 0, v[114:115]
	global_store_dwordx4 v[68:69], v[64:67], off nt
	s_nop 1
	v_fmamk_f32 v64, v161, 0x3a800000, v235
	v_cmp_gt_f32_e32 vcc, s86, v64
	v_mul_f32_e32 v66, 0x4b800000, v64
	v_add_u32_e32 v65, 0x80, v154
	v_cndmask_b32_e32 v64, v64, v66, vcc
	v_rsq_f32_e32 v64, v64
	s_nop 0
	v_mul_f32_e32 v66, 0x45800000, v64
	v_cndmask_b32_e32 v64, v64, v66, vcc
	v_mul_f32_e32 v70, 0xbfb8aa3b, v64
	v_mul_f32_e32 v67, v70, v48
	v_exp_f32_e32 v67, v67
	v_mul_f32_e32 v66, v70, v52
	v_exp_f32_e32 v66, v66
	v_mul_f32_e32 v64, v64, v64
	v_add_f32_e32 v67, 1.0, v67
	v_rcp_f32_e32 v68, v67
	v_mul_f32_e32 v67, v70, v53
	v_exp_f32_e32 v67, v67
	v_add_f32_e32 v66, 1.0, v66
	v_rcp_f32_e32 v66, v66
	v_pk_mul_f32 v[52:53], v[52:53], v[60:61]
	v_add_f32_e32 v67, 1.0, v67
	v_rcp_f32_e32 v67, v67
	s_nop 0
	v_pk_mul_f32 v[60:61], v[64:65], v[66:67] op_sel_hi:[0,1]
	v_pk_mul_f32 v[52:53], v[60:61], v[52:53]
	v_mul_f32_e32 v60, v70, v49
	v_exp_f32_e32 v60, v60
	v_pk_mul_f32 v[48:49], v[48:49], v[56:57]
	v_add_f32_e32 v60, 1.0, v60
	v_rcp_f32_e32 v69, v60
	s_nop 0
	v_pk_mul_f32 v[56:57], v[64:65], v[68:69] op_sel_hi:[0,1]
	v_pk_mul_f32 v[56:57], v[56:57], v[48:49]
	v_mul_f32_e32 v49, v70, v50
	v_exp_f32_e32 v49, v49
	v_mul_f32_e32 v48, v70, v54
	v_exp_f32_e32 v48, v48
	v_add_f32_e32 v49, 1.0, v49
	v_rcp_f32_e32 v50, v49
	v_mul_f32_e32 v49, v70, v55
	v_exp_f32_e32 v49, v49
	v_add_f32_e32 v48, 1.0, v48
	v_rcp_f32_e32 v48, v48
	v_add_f32_e32 v49, 1.0, v49
	v_rcp_f32_e32 v49, v49
	s_nop 0
	v_pk_mul_f32 v[48:49], v[64:65], v[48:49] op_sel_hi:[0,1]
	v_pk_mul_f32 v[54:55], v[48:49], v[62:63]
	v_mul_f32_e32 v48, v70, v51
	v_exp_f32_e32 v48, v48
	s_nop 0
	v_add_f32_e32 v48, 1.0, v48
	v_rcp_f32_e32 v51, v48
	s_nop 0
	v_pk_mul_f32 v[48:49], v[64:65], v[50:51] op_sel_hi:[0,1]
	v_pk_mul_f32 v[58:59], v[48:49], v[58:59]
	v_cvt_pk_bf16_f32 v48, v52, v53
	v_mad_i64_i32 v[52:53], s[0:1], v65, s9, v[112:113]
	v_cvt_pk_bf16_f32 v49, v54, v55
	v_cvt_pk_bf16_f32 v50, v56, v57
	v_cvt_pk_bf16_f32 v51, v58, v59
	v_lshl_add_u64 v[52:53], v[52:53], 0, v[114:115]
	global_store_dwordx4 v[52:53], v[48:51], off nt
	s_nop 1
	v_fmamk_f32 v48, v160, 0x3a800000, v235
	v_cmp_gt_f32_e32 vcc, s86, v48
	v_mul_f32_e32 v49, 0x4b800000, v48
	s_nop 0
	v_cndmask_b32_e32 v48, v48, v49, vcc
	v_rsq_f32_e32 v48, v48
	s_nop 0
	v_mul_f32_e32 v49, 0x45800000, v48
	v_cndmask_b32_e32 v48, v48, v49, vcc
	v_mul_f32_e32 v49, 0xbfb8aa3b, v48
	v_mul_f32_e32 v51, v49, v32
	v_exp_f32_e32 v51, v51
	v_mul_f32_e32 v50, v49, v36
	v_exp_f32_e32 v50, v50
	v_mul_f32_e32 v48, v48, v48
	v_add_f32_e32 v51, 1.0, v51
	v_rcp_f32_e32 v52, v51
	v_mul_f32_e32 v51, v49, v37
	v_exp_f32_e32 v51, v51
	v_add_f32_e32 v50, 1.0, v50
	v_rcp_f32_e32 v50, v50
	v_pk_mul_f32 v[36:37], v[36:37], v[44:45]
	v_add_f32_e32 v51, 1.0, v51
	v_rcp_f32_e32 v51, v51
	s_nop 0
	v_pk_mul_f32 v[44:45], v[48:49], v[50:51] op_sel_hi:[0,1]
	v_pk_mul_f32 v[36:37], v[44:45], v[36:37]
	v_mul_f32_e32 v44, v49, v33
	v_exp_f32_e32 v44, v44
	v_pk_mul_f32 v[32:33], v[32:33], v[40:41]
	v_add_f32_e32 v44, 1.0, v44
	v_rcp_f32_e32 v53, v44
	v_add_u32_e32 v44, 0x90, v154
	v_pk_mul_f32 v[40:41], v[48:49], v[52:53] op_sel_hi:[0,1]
	v_pk_mul_f32 v[40:41], v[40:41], v[32:33]
	v_mul_f32_e32 v33, v49, v34
	v_exp_f32_e32 v33, v33
	v_mul_f32_e32 v32, v49, v38
	v_exp_f32_e32 v32, v32
	v_add_f32_e32 v33, 1.0, v33
	v_rcp_f32_e32 v34, v33
	v_mul_f32_e32 v33, v49, v39
	v_exp_f32_e32 v33, v33
	v_add_f32_e32 v32, 1.0, v32
	v_rcp_f32_e32 v32, v32
	v_add_f32_e32 v33, 1.0, v33
	v_rcp_f32_e32 v33, v33
	s_nop 0
	v_pk_mul_f32 v[32:33], v[48:49], v[32:33] op_sel_hi:[0,1]
	v_pk_mul_f32 v[38:39], v[32:33], v[46:47]
	v_mul_f32_e32 v32, v49, v35
	v_exp_f32_e32 v32, v32
	s_nop 0
	v_add_f32_e32 v32, 1.0, v32
	v_rcp_f32_e32 v35, v32
	s_nop 0
	v_pk_mul_f32 v[32:33], v[48:49], v[34:35] op_sel_hi:[0,1]
	v_pk_mul_f32 v[42:43], v[32:33], v[42:43]
	v_cvt_pk_bf16_f32 v32, v36, v37
	v_mad_i64_i32 v[36:37], s[0:1], v44, s9, v[112:113]
	v_cvt_pk_bf16_f32 v33, v38, v39
	v_cvt_pk_bf16_f32 v34, v40, v41
	v_cvt_pk_bf16_f32 v35, v42, v43
	v_lshl_add_u64 v[36:37], v[36:37], 0, v[114:115]
	global_store_dwordx4 v[36:37], v[32:35], off nt
	s_nop 1
	v_fmamk_f32 v32, v159, 0x3a800000, v235
	v_cmp_gt_f32_e32 vcc, s86, v32
	v_mul_f32_e32 v33, 0x4b800000, v32
	s_nop 0
	v_cndmask_b32_e32 v32, v32, v33, vcc
	v_rsq_f32_e32 v32, v32
	s_nop 0
	v_mul_f32_e32 v33, 0x45800000, v32
	v_cndmask_b32_e32 v32, v32, v33, vcc
	v_mul_f32_e32 v33, 0xbfb8aa3b, v32
	v_mul_f32_e32 v35, v33, v16
	v_exp_f32_e32 v35, v35
	v_mul_f32_e32 v34, v33, v20
	v_exp_f32_e32 v34, v34
	v_mul_f32_e32 v32, v32, v32
	v_add_f32_e32 v35, 1.0, v35
	v_rcp_f32_e32 v36, v35
	v_mul_f32_e32 v35, v33, v21
	v_exp_f32_e32 v35, v35
	v_add_f32_e32 v34, 1.0, v34
	v_rcp_f32_e32 v34, v34
	v_pk_mul_f32 v[20:21], v[20:21], v[28:29]
	v_add_f32_e32 v35, 1.0, v35
	v_rcp_f32_e32 v35, v35
	s_nop 0
	v_pk_mul_f32 v[28:29], v[32:33], v[34:35] op_sel_hi:[0,1]
	v_pk_mul_f32 v[20:21], v[28:29], v[20:21]
	v_mul_f32_e32 v28, v33, v17
	v_exp_f32_e32 v28, v28
	v_pk_mul_f32 v[16:17], v[16:17], v[24:25]
	v_add_f32_e32 v28, 1.0, v28
	v_rcp_f32_e32 v37, v28
	v_add_u32_e32 v28, 0xa0, v154
	v_pk_mul_f32 v[24:25], v[32:33], v[36:37] op_sel_hi:[0,1]
	v_pk_mul_f32 v[24:25], v[24:25], v[16:17]
	v_mul_f32_e32 v17, v33, v18
	v_exp_f32_e32 v17, v17
	v_mul_f32_e32 v16, v33, v22
	v_exp_f32_e32 v16, v16
	v_add_f32_e32 v17, 1.0, v17
	v_rcp_f32_e32 v18, v17
	v_mul_f32_e32 v17, v33, v23
	v_exp_f32_e32 v17, v17
	v_add_f32_e32 v16, 1.0, v16
	v_rcp_f32_e32 v16, v16
	v_add_f32_e32 v17, 1.0, v17
	v_rcp_f32_e32 v17, v17
	s_nop 0
	v_pk_mul_f32 v[16:17], v[32:33], v[16:17] op_sel_hi:[0,1]
	v_pk_mul_f32 v[22:23], v[16:17], v[30:31]
	v_mul_f32_e32 v16, v33, v19
	v_exp_f32_e32 v16, v16
	s_nop 0
	v_add_f32_e32 v16, 1.0, v16
	v_rcp_f32_e32 v19, v16
	s_nop 0
	v_pk_mul_f32 v[16:17], v[32:33], v[18:19] op_sel_hi:[0,1]
	v_pk_mul_f32 v[26:27], v[16:17], v[26:27]
	v_cvt_pk_bf16_f32 v16, v20, v21
	v_mad_i64_i32 v[20:21], s[0:1], v28, s9, v[112:113]
	v_cvt_pk_bf16_f32 v17, v22, v23
	v_cvt_pk_bf16_f32 v18, v24, v25
	v_cvt_pk_bf16_f32 v19, v26, v27
	v_lshl_add_u64 v[20:21], v[20:21], 0, v[114:115]
	global_store_dwordx4 v[20:21], v[16:19], off nt
	s_nop 1
	v_fmamk_f32 v16, v155, 0x3a800000, v235
	v_cmp_gt_f32_e32 vcc, s86, v16
	v_mul_f32_e32 v17, 0x4b800000, v16
	s_nop 0
	v_cndmask_b32_e32 v16, v16, v17, vcc
	v_rsq_f32_e32 v16, v16
	s_nop 0
	v_mul_f32_e32 v17, 0x45800000, v16
	v_cndmask_b32_e32 v16, v16, v17, vcc
	v_mul_f32_e32 v17, 0xbfb8aa3b, v16
	v_mul_f32_e32 v19, v17, v0
	v_exp_f32_e32 v19, v19
	v_mul_f32_e32 v18, v17, v4
	v_exp_f32_e32 v18, v18
	v_mul_f32_e32 v16, v16, v16
	v_add_f32_e32 v19, 1.0, v19
	v_rcp_f32_e32 v20, v19
	v_mul_f32_e32 v19, v17, v5
	v_exp_f32_e32 v19, v19
	v_add_f32_e32 v18, 1.0, v18
	v_rcp_f32_e32 v18, v18
	v_pk_mul_f32 v[4:5], v[4:5], v[12:13]
	v_add_f32_e32 v19, 1.0, v19
	v_rcp_f32_e32 v19, v19
	s_and_b64 vcc, exec, s[38:39]
	v_pk_mul_f32 v[12:13], v[16:17], v[18:19] op_sel_hi:[0,1]
	v_pk_mul_f32 v[4:5], v[12:13], v[4:5]
	v_mul_f32_e32 v12, v17, v1
	v_exp_f32_e32 v12, v12
	v_pk_mul_f32 v[0:1], v[0:1], v[8:9]
	v_add_f32_e32 v12, 1.0, v12
	v_rcp_f32_e32 v21, v12
	v_add_u32_e32 v12, 0xb0, v154
	v_pk_mul_f32 v[8:9], v[16:17], v[20:21] op_sel_hi:[0,1]
	v_pk_mul_f32 v[8:9], v[8:9], v[0:1]
	v_mul_f32_e32 v1, v17, v2
	v_exp_f32_e32 v1, v1
	v_mul_f32_e32 v0, v17, v6
	v_exp_f32_e32 v0, v0
	v_add_f32_e32 v1, 1.0, v1
	v_rcp_f32_e32 v2, v1
	v_mul_f32_e32 v1, v17, v7
	v_exp_f32_e32 v1, v1
	v_add_f32_e32 v0, 1.0, v0
	v_rcp_f32_e32 v0, v0
	v_add_f32_e32 v1, 1.0, v1
	v_rcp_f32_e32 v1, v1
	s_nop 0
	v_pk_mul_f32 v[0:1], v[16:17], v[0:1] op_sel_hi:[0,1]
	v_pk_mul_f32 v[6:7], v[0:1], v[14:15]
	v_mul_f32_e32 v0, v17, v3
	v_exp_f32_e32 v0, v0
	s_nop 0
	v_add_f32_e32 v0, 1.0, v0
	v_rcp_f32_e32 v3, v0
	s_nop 0
	v_pk_mul_f32 v[0:1], v[16:17], v[2:3] op_sel_hi:[0,1]
	v_pk_mul_f32 v[10:11], v[0:1], v[10:11]
	v_cvt_pk_bf16_f32 v0, v4, v5
	v_mad_i64_i32 v[4:5], s[0:1], v12, s9, v[112:113]
	v_cvt_pk_bf16_f32 v1, v6, v7
	v_cvt_pk_bf16_f32 v2, v8, v9
	v_cvt_pk_bf16_f32 v3, v10, v11
	v_lshl_add_u64 v[4:5], v[4:5], 0, v[114:115]
	s_mov_b32 s0, s8
	global_store_dwordx4 v[4:5], v[0:3], off nt
	s_cbranch_vccz .LBB0_388
	s_waitcnt vmcnt(0)
	v_readlane_b32 s20, v255, 27
